# nt2 + nt hint on P11 h-row loads and the read-once residual loads of the P13 and P10 GEMM epilogues
# speedup vs baseline: 1.0009x; 1.0009x over previous
; __device__ __forceinline__ u32x4 pack8(const f32x4 v0, const f32x4 v1) { u32x4 w; w.x = cvt_pk_bf16(v0[0], v0[1]); w.y = cvt_pk_bf16(v0[2], v0[3]); w.z = cvt_pk_bf16(v1[0], v1[1]); w.w = cvt_pk_bf16(v1[2], v1[3]); return w; }
; __device__ __forceinline__ void unpack8(const u32x4 w, f32x4& v0, f32x4& v1) { v0 = (f32x4){bf_lo(w.x), bf_hi(w.x), bf_lo(w.y), bf_hi(w.y)}; v1 = (f32x4){bf_lo(w.z), bf_hi(w.z), bf_lo(w.w), bf_hi(w.w)}; }
;     __device__ __forceinline__ void operator()(const f32x4 (&acc)[2][2][4][2], const Unit& u, int wr, int wc, int fr, int fq) const {
;         const int row0 = u.pm * BM + wr * 64 + fr, col0 = u.pn * BM + wc * 32 + 8 * fq;
; #pragma unroll
;         for (int ai = 0; ai < 2; ++ai)
; #pragma unroll
;             for (int m = 0; m < 4; ++m) { const int row = row0 + ai * HALF + m * 16;
;                 const size_t bo = base_grp_rows ? (size_t)(row / base_grp_rows) * base_grp_stride + (size_t)(row % base_grp_rows) * ldc : (size_t)row * ldc;
;                 const size_t oo = out_grp_rows ? (size_t)(row / out_grp_rows) * out_grp_stride + (size_t)(row % out_grp_rows) * ldc : (size_t)row * ldc;
; #pragma unroll
;                 for (int bj = 0; bj < 2; ++bj) { const int col = col0 + bj * HALF;
;                     f32x4 b0, b1;
;                     if constexpr (BASE_BF) unpack8(*(const u32x4*)((const bf16_t*)base + bo + col), b0, b1);
;                     else { b0 = *(const f32x4*)((const float*)base + bo + col); b1 = *(const f32x4*)((const float*)base + bo + col + 4); }
;                     *(u32x4*)(out + oo + col) = pack8(b0 + acc[ai][bj][m][0] * scale, b1 + acc[ai][bj][m][1] * scale); } }
;     ...
;         if constexpr (I8) { typedef int v4i_ __attribute__((ext_vector_type(4)));
; #pragma unroll
;             for (int a = 0; a < 2; ++a)
; #pragma unroll
;                 for (int b = 0; b < 2; ++b)
; #pragma unroll
;                     for (int m = 0; m < 4; ++m)
; #pragma unroll
;                         for (int n = 0; n < 2; ++n) { const v4i_ c_ = __builtin_bit_cast(v4i_, acc[a][b][m][n]); acc[a][b][m][n] = (f32x4){(float)c_[0], (float)c_[1], (float)c_[2], (float)c_[3]}; } }
.LBB0_915:
	v_cvt_f32_i32_e32 v152, v126
	v_cvt_f32_i32_e32 v126, v98
	v_cvt_f32_i32_e32 v98, v92
	v_cvt_f32_i32_e32 v92, v88
	v_cvt_f32_i32_e32 v88, v78
	v_cvt_f32_i32_e32 v78, v74
	v_cvt_f32_i32_e32 v74, v68
	v_cvt_f32_i32_e32 v68, v64
	v_cvt_f32_i32_e32 v64, v30
	v_lshl_add_u32 v30, s73, 8, v157
	v_cvt_f32_i32_e32 v150, v130
	v_cvt_f32_i32_e32 v130, v124
	v_cvt_f32_i32_e32 v153, v127
	v_cvt_f32_i32_e32 v124, v96
	v_cvt_f32_i32_e32 v127, v99
	v_cvt_f32_i32_e32 v99, v93
	v_cvt_f32_i32_e32 v93, v89
	v_cvt_f32_i32_e32 v96, v86
	v_cvt_f32_i32_e32 v86, v82
	v_cvt_f32_i32_e32 v82, v76
	v_cvt_f32_i32_e32 v89, v79
	v_cvt_f32_i32_e32 v76, v72
	v_cvt_f32_i32_e32 v79, v75
	v_cvt_f32_i32_e32 v75, v69
	v_cvt_f32_i32_e32 v69, v65
	v_cvt_f32_i32_e32 v72, v62
	v_cvt_f32_i32_e32 v62, v34
	v_cvt_f32_i32_e32 v34, v28
	v_cvt_f32_i32_e32 v65, v31
	v_lshl_or_b32 v28, s74, 8, v159
	v_ashrrev_i32_e32 v31, 31, v30
	v_cvt_f32_i32_e32 v149, v129
	v_cvt_f32_i32_e32 v148, v128
	v_cvt_f32_i32_e32 v151, v131
	v_cvt_f32_i32_e32 v131, v125
	v_cvt_f32_i32_e32 v125, v97
	v_cvt_f32_i32_e32 v129, v95
	v_cvt_f32_i32_e32 v128, v94
	v_cvt_f32_i32_e32 v95, v91
	v_cvt_f32_i32_e32 v94, v90
	v_cvt_f32_i32_e32 v91, v85
	v_cvt_f32_i32_e32 v90, v84
	v_cvt_f32_i32_e32 v97, v87
	v_cvt_f32_i32_e32 v85, v81
	v_cvt_f32_i32_e32 v84, v80
	v_cvt_f32_i32_e32 v87, v83
	v_cvt_f32_i32_e32 v83, v77
	v_cvt_f32_i32_e32 v77, v73
	v_cvt_f32_i32_e32 v81, v71
	v_cvt_f32_i32_e32 v80, v70
	v_cvt_f32_i32_e32 v71, v67
	v_cvt_f32_i32_e32 v70, v66
	v_cvt_f32_i32_e32 v67, v61
	v_cvt_f32_i32_e32 v66, v60
	v_cvt_f32_i32_e32 v73, v63
	v_cvt_f32_i32_e32 v61, v33
	v_cvt_f32_i32_e32 v60, v32
	v_cvt_f32_i32_e32 v63, v35
	v_cvt_f32_i32_e32 v35, v29
	v_lshlrev_b64 v[32:33], 14, v[30:31]
	v_ashrrev_i32_e32 v29, 31, v28
	v_lshl_add_u64 v[154:155], s[34:35], 0, v[32:33]
	v_lshlrev_b64 v[32:33], 2, v[28:29]
	v_lshl_add_u64 v[154:155], v[154:155], 0, v[32:33]
	global_load_dwordx4 v[162:165], v[154:155], off offset:16 nt
	global_load_dwordx4 v[166:169], v[154:155], off nt
	v_lshlrev_b64 v[28:29], 1, v[28:29]
	v_cvt_f32_i32_e32 v117, v117
	v_cvt_f32_i32_e32 v116, v116
	v_cvt_f32_i32_e32 v119, v119
	v_cvt_f32_i32_e32 v118, v118
	v_cvt_f32_i32_e32 v121, v121
	v_cvt_f32_i32_e32 v120, v120
	v_cvt_f32_i32_e32 v123, v123
	v_cvt_f32_i32_e32 v122, v122
	v_cvt_f32_i32_e32 v113, v113
	v_cvt_f32_i32_e32 v112, v112
	v_cvt_f32_i32_e32 v109, v109
	v_cvt_f32_i32_e32 v108, v108
	v_cvt_f32_i32_e32 v111, v111
	v_cvt_f32_i32_e32 v110, v110
	v_cvt_f32_i32_e32 v115, v115
	v_cvt_f32_i32_e32 v114, v114
	v_cvt_f32_i32_e32 v105, v105
	v_cvt_f32_i32_e32 v104, v104
	v_cvt_f32_i32_e32 v101, v101
	v_cvt_f32_i32_e32 v100, v100
	v_cvt_f32_i32_e32 v103, v103
	v_cvt_f32_i32_e32 v102, v102
	v_cvt_f32_i32_e32 v107, v107
	v_cvt_f32_i32_e32 v106, v106
	v_cvt_f32_i32_e32 v53, v53
	v_cvt_f32_i32_e32 v52, v52
	v_cvt_f32_i32_e32 v55, v55
	v_cvt_f32_i32_e32 v54, v54
	v_cvt_f32_i32_e32 v57, v57
	v_cvt_f32_i32_e32 v56, v56
	v_cvt_f32_i32_e32 v59, v59
	v_cvt_f32_i32_e32 v58, v58
	v_cvt_f32_i32_e32 v21, v21
	v_cvt_f32_i32_e32 v20, v20
	v_cvt_f32_i32_e32 v23, v23
	v_cvt_f32_i32_e32 v22, v22
	v_cvt_f32_i32_e32 v25, v25
	v_cvt_f32_i32_e32 v24, v24
	v_cvt_f32_i32_e32 v27, v27
	v_cvt_f32_i32_e32 v26, v26
	v_cvt_f32_i32_e32 v49, v49
	v_cvt_f32_i32_e32 v48, v48
	v_cvt_f32_i32_e32 v45, v45
	v_cvt_f32_i32_e32 v44, v44
	v_cvt_f32_i32_e32 v47, v47
	v_cvt_f32_i32_e32 v46, v46
	v_cvt_f32_i32_e32 v51, v51
	v_cvt_f32_i32_e32 v50, v50
	v_cvt_f32_i32_e32 v13, v13
	v_cvt_f32_i32_e32 v12, v12
	v_cvt_f32_i32_e32 v15, v15
	v_cvt_f32_i32_e32 v14, v14
	v_cvt_f32_i32_e32 v17, v17
	v_cvt_f32_i32_e32 v16, v16
	v_cvt_f32_i32_e32 v19, v19
	v_cvt_f32_i32_e32 v18, v18
	v_cvt_f32_i32_e32 v41, v41
	v_cvt_f32_i32_e32 v40, v40
	v_cvt_f32_i32_e32 v37, v37
	v_cvt_f32_i32_e32 v36, v36
	v_cvt_f32_i32_e32 v39, v39
	v_cvt_f32_i32_e32 v38, v38
	v_cvt_f32_i32_e32 v43, v43
	v_cvt_f32_i32_e32 v42, v42
	v_cvt_f32_i32_e32 v5, v5
	v_cvt_f32_i32_e32 v4, v4
	v_cvt_f32_i32_e32 v7, v7
	v_cvt_f32_i32_e32 v6, v6
	v_cvt_f32_i32_e32 v9, v9
	v_cvt_f32_i32_e32 v8, v8
	v_cvt_f32_i32_e32 v11, v11
	v_cvt_f32_i32_e32 v10, v10
	s_mov_b64 s[38:39], -1
	s_and_b64 vcc, exec, s[36:37]
	s_waitcnt vmcnt(0)
	v_pk_fma_f32 v[130:131], v[130:131], s[26:27], v[162:163] op_sel_hi:[1,0,1]
	v_pk_fma_f32 v[150:151], v[150:151], s[26:27], v[168:169] op_sel_hi:[1,0,1]
	v_pk_fma_f32 v[148:149], v[148:149], s[26:27], v[166:167] op_sel_hi:[1,0,1]
	v_pk_fma_f32 v[152:153], v[152:153], s[26:27], v[164:165] op_sel_hi:[1,0,1]
	v_cvt_pk_bf16_f32 v148, v148, v149
	v_cvt_pk_bf16_f32 v149, v150, v151
	v_cvt_pk_bf16_f32 v150, v130, v131
	v_lshlrev_b64 v[130:131], 13, v[30:31]
	v_lshl_add_u64 v[130:131], s[48:49], 0, v[130:131]
	v_lshl_add_u64 v[130:131], v[130:131], 0, v[28:29]
	v_cvt_pk_bf16_f32 v151, v152, v153
	global_store_dwordx4 v[130:131], v[148:151], off
	global_load_dwordx4 v[148:151], v[154:155], off offset:528 nt
	s_nop 0
	global_load_dwordx4 v[152:155], v[154:155], off offset:512 nt
	s_waitcnt vmcnt(1)
	v_pk_fma_f32 v[98:99], v[98:99], s[26:27], v[148:149] op_sel_hi:[1,0,1]
	s_waitcnt vmcnt(0)
	v_pk_fma_f32 v[126:127], v[126:127], s[26:27], v[154:155] op_sel_hi:[1,0,1]
	v_pk_fma_f32 v[124:125], v[124:125], s[26:27], v[152:153] op_sel_hi:[1,0,1]
	v_pk_fma_f32 v[128:129], v[128:129], s[26:27], v[150:151] op_sel_hi:[1,0,1]
	v_cvt_pk_bf16_f32 v124, v124, v125
	v_cvt_pk_bf16_f32 v125, v126, v127
	v_cvt_pk_bf16_f32 v126, v98, v99
	v_or_b32_e32 v98, 16, v30
	v_ashrrev_i32_e32 v99, 31, v98
	v_cvt_pk_bf16_f32 v127, v128, v129
	global_store_dwordx4 v[130:131], v[124:127], off offset:256
	s_nop 1
	v_lshlrev_b64 v[124:125], 14, v[98:99]
	v_lshl_add_u64 v[124:125], s[34:35], 0, v[124:125]
	v_lshl_add_u64 v[148:149], v[124:125], 0, v[32:33]
	global_load_dwordx4 v[124:127], v[148:149], off offset:16 nt
	global_load_dwordx4 v[128:131], v[148:149], off nt
	v_lshlrev_b64 v[98:99], 13, v[98:99]
	v_lshl_add_u64 v[98:99], s[48:49], 0, v[98:99]
	v_lshl_add_u64 v[98:99], v[98:99], 0, v[28:29]
	s_waitcnt vmcnt(1)
; __device__ __forceinline__ u32x4 pack8(const f32x4 v0, const f32x4 v1) { u32x4 w; w.x = cvt_pk_bf16(v0[0], v0[1]); w.y = cvt_pk_bf16(v0[2], v0[3]); w.z = cvt_pk_bf16(v1[0], v1[1]); w.w = cvt_pk_bf16(v1[2], v1[3]); return w; }
; __device__ __forceinline__ void unpack8(const u32x4 w, f32x4& v0, f32x4& v1) { v0 = (f32x4){bf_lo(w.x), bf_hi(w.x), bf_lo(w.y), bf_hi(w.y)}; v1 = (f32x4){bf_lo(w.z), bf_hi(w.z), bf_lo(w.w), bf_hi(w.w)}; }
;     __device__ __forceinline__ void operator()(const f32x4 (&acc)[2][2][4][2], const Unit& u, int wr, int wc, int fr, int fq) const {
;     ...
;             for (int m = 0; m < 4; ++m) { const int row = row0 + ai * HALF + m * 16;
;                 const size_t bo = base_grp_rows ? (size_t)(row / base_grp_rows) * base_grp_stride + (size_t)(row % base_grp_rows) * ldc : (size_t)row * ldc;
;                 const size_t oo = out_grp_rows ? (size_t)(row / out_grp_rows) * out_grp_stride + (size_t)(row % out_grp_rows) * ldc : (size_t)row * ldc;
; #pragma unroll
;                 for (int bj = 0; bj < 2; ++bj) { const int col = col0 + bj * HALF;
;                     f32x4 b0, b1;
;                     if constexpr (BASE_BF) unpack8(*(const u32x4*)((const bf16_t*)base + bo + col), b0, b1);
;                     else { b0 = *(const f32x4*)((const float*)base + bo + col); b1 = *(const f32x4*)((const float*)base + bo + col + 4); }
;                     *(u32x4*)(out + oo + col) = pack8(b0 + acc[ai][bj][m][0] * scale, b1 + acc[ai][bj][m][1] * scale); } }
	v_pk_fma_f32 v[126:127], v[118:119], s[26:27], v[126:127] op_sel_hi:[1,0,1]
	v_pk_fma_f32 v[118:119], v[116:117], s[26:27], v[124:125] op_sel_hi:[1,0,1]
	s_waitcnt vmcnt(0)
	v_pk_fma_f32 v[122:123], v[122:123], s[26:27], v[130:131] op_sel_hi:[1,0,1]
	v_pk_fma_f32 v[120:121], v[120:121], s[26:27], v[128:129] op_sel_hi:[1,0,1]
	s_nop 0
	v_cvt_pk_bf16_f32 v116, v120, v121
	v_cvt_pk_bf16_f32 v117, v122, v123
	v_cvt_pk_bf16_f32 v118, v118, v119
	v_cvt_pk_bf16_f32 v119, v126, v127
	global_store_dwordx4 v[98:99], v[116:119], off
	global_load_dwordx4 v[116:119], v[148:149], off offset:528 nt
	s_nop 0
	global_load_dwordx4 v[120:123], v[148:149], off offset:512 nt
	s_waitcnt vmcnt(1)
	v_pk_fma_f32 v[96:97], v[96:97], s[26:27], v[118:119] op_sel_hi:[1,0,1]
	s_waitcnt vmcnt(0)
	v_pk_fma_f32 v[92:93], v[92:93], s[26:27], v[120:121] op_sel_hi:[1,0,1]
	v_pk_fma_f32 v[94:95], v[94:95], s[26:27], v[122:123] op_sel_hi:[1,0,1]
	v_pk_fma_f32 v[116:117], v[90:91], s[26:27], v[116:117] op_sel_hi:[1,0,1]
	v_cvt_pk_bf16_f32 v90, v92, v93
	v_cvt_pk_bf16_f32 v91, v94, v95
	s_nop 0
	v_cvt_pk_bf16_f32 v92, v116, v117
	v_cvt_pk_bf16_f32 v93, v96, v97
	global_store_dwordx4 v[98:99], v[90:93], off offset:256
	v_or_b32_e32 v98, 32, v30
	v_ashrrev_i32_e32 v99, 31, v98
	v_lshlrev_b64 v[90:91], 14, v[98:99]
	v_lshl_add_u64 v[90:91], s[34:35], 0, v[90:91]
	v_lshl_add_u64 v[116:117], v[90:91], 0, v[32:33]
	global_load_dwordx4 v[90:93], v[116:117], off offset:16 nt
	global_load_dwordx4 v[94:97], v[116:117], off nt
	s_waitcnt vmcnt(1)
	v_pk_fma_f32 v[110:111], v[110:111], s[26:27], v[92:93] op_sel_hi:[1,0,1]
	s_waitcnt vmcnt(0)
	v_pk_fma_f32 v[94:95], v[112:113], s[26:27], v[94:95] op_sel_hi:[1,0,1]
	v_pk_fma_f32 v[92:93], v[108:109], s[26:27], v[90:91] op_sel_hi:[1,0,1]
	v_cvt_pk_bf16_f32 v90, v94, v95
	v_lshlrev_b64 v[94:95], 13, v[98:99]
	v_lshl_add_u64 v[94:95], s[48:49], 0, v[94:95]
	v_lshl_add_u64 v[98:99], v[94:95], 0, v[28:29]
	v_pk_fma_f32 v[96:97], v[114:115], s[26:27], v[96:97] op_sel_hi:[1,0,1]
	s_nop 0
	v_cvt_pk_bf16_f32 v91, v96, v97
	v_cvt_pk_bf16_f32 v92, v92, v93
	v_cvt_pk_bf16_f32 v93, v110, v111
	global_store_dwordx4 v[98:99], v[90:93], off
	global_load_dwordx4 v[90:93], v[116:117], off offset:528 nt
	s_nop 0
	global_load_dwordx4 v[94:97], v[116:117], off offset:512 nt
	s_waitcnt vmcnt(1)
	v_pk_fma_f32 v[90:91], v[82:83], s[26:27], v[90:91] op_sel_hi:[1,0,1]
	s_waitcnt vmcnt(0)
	v_pk_fma_f32 v[84:85], v[84:85], s[26:27], v[94:95] op_sel_hi:[1,0,1]
	v_pk_fma_f32 v[86:87], v[86:87], s[26:27], v[96:97] op_sel_hi:[1,0,1]
	v_cvt_pk_bf16_f32 v82, v84, v85
	v_pk_fma_f32 v[88:89], v[88:89], s[26:27], v[92:93] op_sel_hi:[1,0,1]
	v_cvt_pk_bf16_f32 v83, v86, v87
	v_cvt_pk_bf16_f32 v84, v90, v91
	v_or_b32_e32 v90, 48, v30
	v_ashrrev_i32_e32 v91, 31, v90
	v_cvt_pk_bf16_f32 v85, v88, v89
	global_store_dwordx4 v[98:99], v[82:85], off offset:256
	s_nop 1
	v_lshlrev_b64 v[82:83], 14, v[90:91]
	v_lshl_add_u64 v[82:83], s[34:35], 0, v[82:83]
	v_lshl_add_u64 v[92:93], v[82:83], 0, v[32:33]
	global_load_dwordx4 v[82:85], v[92:93], off offset:16 nt
	global_load_dwordx4 v[86:89], v[92:93], off nt
	s_waitcnt vmcnt(1)
	v_pk_fma_f32 v[94:95], v[102:103], s[26:27], v[84:85] op_sel_hi:[1,0,1]
	s_waitcnt vmcnt(0)
	v_pk_fma_f32 v[86:87], v[104:105], s[26:27], v[86:87] op_sel_hi:[1,0,1]
	v_pk_fma_f32 v[84:85], v[100:101], s[26:27], v[82:83] op_sel_hi:[1,0,1]
	v_cvt_pk_bf16_f32 v82, v86, v87
	v_lshlrev_b64 v[86:87], 13, v[90:91]
	v_lshl_add_u64 v[86:87], s[48:49], 0, v[86:87]
	v_lshl_add_u64 v[90:91], v[86:87], 0, v[28:29]
	v_pk_fma_f32 v[88:89], v[106:107], s[26:27], v[88:89] op_sel_hi:[1,0,1]
	s_nop 0
	v_cvt_pk_bf16_f32 v83, v88, v89
	v_cvt_pk_bf16_f32 v84, v84, v85
	v_cvt_pk_bf16_f32 v85, v94, v95
	global_store_dwordx4 v[90:91], v[82:85], off
	global_load_dwordx4 v[82:85], v[92:93], off offset:528 nt
	s_nop 0
	global_load_dwordx4 v[86:89], v[92:93], off offset:512 nt
	s_waitcnt vmcnt(1)
	v_pk_fma_f32 v[82:83], v[74:75], s[26:27], v[82:83] op_sel_hi:[1,0,1]
	s_waitcnt vmcnt(0)
	v_pk_fma_f32 v[76:77], v[76:77], s[26:27], v[86:87] op_sel_hi:[1,0,1]
	v_pk_fma_f32 v[78:79], v[78:79], s[26:27], v[88:89] op_sel_hi:[1,0,1]
	v_cvt_pk_bf16_f32 v74, v76, v77
	v_pk_fma_f32 v[80:81], v[80:81], s[26:27], v[84:85] op_sel_hi:[1,0,1]
	v_cvt_pk_bf16_f32 v75, v78, v79
	v_cvt_pk_bf16_f32 v76, v82, v83
	v_add_u32_e32 v82, 0x80, v30
	v_ashrrev_i32_e32 v83, 31, v82
	v_cvt_pk_bf16_f32 v77, v80, v81
	global_store_dwordx4 v[90:91], v[74:77], off offset:256
	s_nop 1
	v_lshlrev_b64 v[74:75], 14, v[82:83]
	v_lshl_add_u64 v[74:75], s[34:35], 0, v[74:75]
	v_lshl_add_u64 v[84:85], v[74:75], 0, v[32:33]
	global_load_dwordx4 v[74:77], v[84:85], off offset:16 nt
	global_load_dwordx4 v[78:81], v[84:85], off nt
	s_waitcnt vmcnt(1)
	v_pk_fma_f32 v[74:75], v[66:67], s[26:27], v[74:75] op_sel_hi:[1,0,1]
	s_waitcnt vmcnt(0)
	v_pk_fma_f32 v[70:71], v[70:71], s[26:27], v[80:81] op_sel_hi:[1,0,1]
	v_pk_fma_f32 v[68:69], v[68:69], s[26:27], v[78:79] op_sel_hi:[1,0,1]
	v_pk_fma_f32 v[72:73], v[72:73], s[26:27], v[76:77] op_sel_hi:[1,0,1]
	v_cvt_pk_bf16_f32 v66, v68, v69
	v_cvt_pk_bf16_f32 v67, v70, v71
	v_lshlrev_b64 v[70:71], 13, v[82:83]
	v_lshl_add_u64 v[70:71], s[48:49], 0, v[70:71]
	v_cvt_pk_bf16_f32 v68, v74, v75
	v_lshl_add_u64 v[74:75], v[70:71], 0, v[28:29]
	v_cvt_pk_bf16_f32 v69, v72, v73
	global_store_dwordx4 v[74:75], v[66:69], off
	global_load_dwordx4 v[66:69], v[84:85], off offset:528 nt
	s_nop 0
	global_load_dwordx4 v[70:73], v[84:85], off offset:512 nt
	s_waitcnt vmcnt(1)
; __device__ __forceinline__ u32x4 pack8(const f32x4 v0, const f32x4 v1) { u32x4 w; w.x = cvt_pk_bf16(v0[0], v0[1]); w.y = cvt_pk_bf16(v0[2], v0[3]); w.z = cvt_pk_bf16(v1[0], v1[1]); w.w = cvt_pk_bf16(v1[2], v1[3]); return w; }
; __device__ __forceinline__ void unpack8(const u32x4 w, f32x4& v0, f32x4& v1) { v0 = (f32x4){bf_lo(w.x), bf_hi(w.x), bf_lo(w.y), bf_hi(w.y)}; v1 = (f32x4){bf_lo(w.z), bf_hi(w.z), bf_lo(w.w), bf_hi(w.w)}; }
; #define PG8_BAR __builtin_amdgcn_s_barrier()
;     __device__ __forceinline__ void operator()(const f32x4 (&acc)[2][2][4][2], const Unit& u, int wr, int wc, int fr, int fq) const {
;     ...
;             for (int m = 0; m < 4; ++m) { const int row = row0 + ai * HALF + m * 16;
;                 const size_t bo = base_grp_rows ? (size_t)(row / base_grp_rows) * base_grp_stride + (size_t)(row % base_grp_rows) * ldc : (size_t)row * ldc;
;                 const size_t oo = out_grp_rows ? (size_t)(row / out_grp_rows) * out_grp_stride + (size_t)(row % out_grp_rows) * ldc : (size_t)row * ldc;
; #pragma unroll
;                 for (int bj = 0; bj < 2; ++bj) { const int col = col0 + bj * HALF;
;                     f32x4 b0, b1;
;                     if constexpr (BASE_BF) unpack8(*(const u32x4*)((const bf16_t*)base + bo + col), b0, b1);
;                     else { b0 = *(const f32x4*)((const float*)base + bo + col); b1 = *(const f32x4*)((const float*)base + bo + col + 4); }
;                     *(u32x4*)(out + oo + col) = pack8(b0 + acc[ai][bj][m][0] * scale, b1 + acc[ai][bj][m][1] * scale); } }
;     ...
;         if (!has_next) break;
; #pragma unroll
;         for (int a = 0; a < 2; ++a)
; #pragma unroll
;             for (int b = 0; b < 2; ++b)
; #pragma unroll
;                 for (int m = 0; m < 4; ++m)
; #pragma unroll
;                     for (int n = 0; n < 2; ++n) acc[a][b][m][n] = (f32x4){0.f, 0.f, 0.f, 0.f};
;         cur = nxt; cA = nA; cB = nB; ++ui;
;         if constexpr (ALIGN_EPI) { if (wr == 1) PG8_BAR; }
	v_pk_fma_f32 v[34:35], v[34:35], s[26:27], v[66:67] op_sel_hi:[1,0,1]
	s_waitcnt vmcnt(0)
	v_pk_fma_f32 v[62:63], v[62:63], s[26:27], v[72:73] op_sel_hi:[1,0,1]
	v_pk_fma_f32 v[60:61], v[60:61], s[26:27], v[70:71] op_sel_hi:[1,0,1]
	v_pk_fma_f32 v[64:65], v[64:65], s[26:27], v[68:69] op_sel_hi:[1,0,1]
	v_cvt_pk_bf16_f32 v60, v60, v61
	v_cvt_pk_bf16_f32 v61, v62, v63
	v_cvt_pk_bf16_f32 v62, v34, v35
	v_add_u32_e32 v34, 0x90, v30
	v_ashrrev_i32_e32 v35, 31, v34
	v_cvt_pk_bf16_f32 v63, v64, v65
	global_store_dwordx4 v[74:75], v[60:63], off offset:256
	s_nop 1
	v_lshlrev_b64 v[60:61], 14, v[34:35]
	v_lshl_add_u64 v[60:61], s[34:35], 0, v[60:61]
	v_lshl_add_u64 v[68:69], v[60:61], 0, v[32:33]
	global_load_dwordx4 v[60:63], v[68:69], off offset:16 nt
	global_load_dwordx4 v[64:67], v[68:69], off nt
	v_lshlrev_b64 v[34:35], 13, v[34:35]
	v_lshl_add_u64 v[34:35], s[48:49], 0, v[34:35]
	v_lshl_add_u64 v[34:35], v[34:35], 0, v[28:29]
	s_waitcnt vmcnt(1)
	v_pk_fma_f32 v[62:63], v[54:55], s[26:27], v[62:63] op_sel_hi:[1,0,1]
	v_pk_fma_f32 v[54:55], v[52:53], s[26:27], v[60:61] op_sel_hi:[1,0,1]
	s_waitcnt vmcnt(0)
	v_pk_fma_f32 v[58:59], v[58:59], s[26:27], v[66:67] op_sel_hi:[1,0,1]
	v_pk_fma_f32 v[56:57], v[56:57], s[26:27], v[64:65] op_sel_hi:[1,0,1]
	s_nop 0
	v_cvt_pk_bf16_f32 v52, v56, v57
	v_cvt_pk_bf16_f32 v53, v58, v59
	v_cvt_pk_bf16_f32 v54, v54, v55
	v_cvt_pk_bf16_f32 v55, v62, v63
	global_store_dwordx4 v[34:35], v[52:55], off
	global_load_dwordx4 v[52:55], v[68:69], off offset:528 nt
	s_nop 0
	global_load_dwordx4 v[56:59], v[68:69], off offset:512 nt
	s_waitcnt vmcnt(1)
	v_pk_fma_f32 v[54:55], v[22:23], s[26:27], v[54:55] op_sel_hi:[1,0,1]
	v_pk_fma_f32 v[22:23], v[20:21], s[26:27], v[52:53] op_sel_hi:[1,0,1]
	s_waitcnt vmcnt(0)
	v_pk_fma_f32 v[26:27], v[26:27], s[26:27], v[58:59] op_sel_hi:[1,0,1]
	v_pk_fma_f32 v[24:25], v[24:25], s[26:27], v[56:57] op_sel_hi:[1,0,1]
	s_nop 0
	v_cvt_pk_bf16_f32 v20, v24, v25
	v_cvt_pk_bf16_f32 v21, v26, v27
	v_cvt_pk_bf16_f32 v22, v22, v23
	v_cvt_pk_bf16_f32 v23, v54, v55
	global_store_dwordx4 v[34:35], v[20:23], off offset:256
	v_add_u32_e32 v34, 0xa0, v30
	v_ashrrev_i32_e32 v35, 31, v34
	v_lshlrev_b64 v[20:21], 14, v[34:35]
	v_lshl_add_u64 v[20:21], s[34:35], 0, v[20:21]
	v_lshl_add_u64 v[52:53], v[20:21], 0, v[32:33]
	global_load_dwordx4 v[20:23], v[52:53], off offset:16 nt
	global_load_dwordx4 v[24:27], v[52:53], off nt
	s_waitcnt vmcnt(1)
	v_pk_fma_f32 v[46:47], v[46:47], s[26:27], v[22:23] op_sel_hi:[1,0,1]
	s_waitcnt vmcnt(0)
	v_pk_fma_f32 v[24:25], v[48:49], s[26:27], v[24:25] op_sel_hi:[1,0,1]
	v_pk_fma_f32 v[22:23], v[44:45], s[26:27], v[20:21] op_sel_hi:[1,0,1]
	v_cvt_pk_bf16_f32 v20, v24, v25
	v_lshlrev_b64 v[24:25], 13, v[34:35]
	v_lshl_add_u64 v[24:25], s[48:49], 0, v[24:25]
	v_lshl_add_u64 v[34:35], v[24:25], 0, v[28:29]
	v_pk_fma_f32 v[26:27], v[50:51], s[26:27], v[26:27] op_sel_hi:[1,0,1]
	s_nop 0
	v_cvt_pk_bf16_f32 v21, v26, v27
	v_cvt_pk_bf16_f32 v22, v22, v23
	v_cvt_pk_bf16_f32 v23, v46, v47
	global_store_dwordx4 v[34:35], v[20:23], off
	global_load_dwordx4 v[20:23], v[52:53], off offset:528 nt
	s_nop 0
	global_load_dwordx4 v[24:27], v[52:53], off offset:512 nt
	s_waitcnt vmcnt(1)
	v_pk_fma_f32 v[22:23], v[14:15], s[26:27], v[22:23] op_sel_hi:[1,0,1]
	v_pk_fma_f32 v[14:15], v[12:13], s[26:27], v[20:21] op_sel_hi:[1,0,1]
	v_add_u32_e32 v20, 0xb0, v30
	s_waitcnt vmcnt(0)
	v_pk_fma_f32 v[18:19], v[18:19], s[26:27], v[26:27] op_sel_hi:[1,0,1]
	v_pk_fma_f32 v[16:17], v[16:17], s[26:27], v[24:25] op_sel_hi:[1,0,1]
	v_ashrrev_i32_e32 v21, 31, v20
	v_cvt_pk_bf16_f32 v12, v16, v17
	v_cvt_pk_bf16_f32 v13, v18, v19
	v_cvt_pk_bf16_f32 v14, v14, v15
	v_cvt_pk_bf16_f32 v15, v22, v23
	global_store_dwordx4 v[34:35], v[12:15], off offset:256
	s_nop 1
	v_lshlrev_b64 v[12:13], 14, v[20:21]
	v_lshl_add_u64 v[12:13], s[34:35], 0, v[12:13]
	v_lshl_add_u64 v[22:23], v[12:13], 0, v[32:33]
	global_load_dwordx4 v[12:15], v[22:23], off offset:16 nt
	global_load_dwordx4 v[16:19], v[22:23], off nt
	s_waitcnt vmcnt(1)
	v_pk_fma_f32 v[24:25], v[38:39], s[26:27], v[14:15] op_sel_hi:[1,0,1]
	s_waitcnt vmcnt(0)
	v_pk_fma_f32 v[16:17], v[40:41], s[26:27], v[16:17] op_sel_hi:[1,0,1]
	v_pk_fma_f32 v[14:15], v[36:37], s[26:27], v[12:13] op_sel_hi:[1,0,1]
	v_cvt_pk_bf16_f32 v12, v16, v17
	v_lshlrev_b64 v[16:17], 13, v[20:21]
	v_lshl_add_u64 v[16:17], s[48:49], 0, v[16:17]
	v_lshl_add_u64 v[20:21], v[16:17], 0, v[28:29]
	v_pk_fma_f32 v[18:19], v[42:43], s[26:27], v[18:19] op_sel_hi:[1,0,1]
	s_nop 0
	v_cvt_pk_bf16_f32 v13, v18, v19
	v_cvt_pk_bf16_f32 v14, v14, v15
	v_cvt_pk_bf16_f32 v15, v24, v25
	global_store_dwordx4 v[20:21], v[12:15], off
	global_load_dwordx4 v[12:15], v[22:23], off offset:528 nt
	s_nop 0
	global_load_dwordx4 v[16:19], v[22:23], off offset:512 nt
	s_waitcnt vmcnt(1)
	v_pk_fma_f32 v[14:15], v[6:7], s[26:27], v[14:15] op_sel_hi:[1,0,1]
	v_pk_fma_f32 v[6:7], v[4:5], s[26:27], v[12:13] op_sel_hi:[1,0,1]
	s_waitcnt vmcnt(0)
	v_pk_fma_f32 v[10:11], v[10:11], s[26:27], v[18:19] op_sel_hi:[1,0,1]
	v_pk_fma_f32 v[8:9], v[8:9], s[26:27], v[16:17] op_sel_hi:[1,0,1]
	s_nop 0
	v_cvt_pk_bf16_f32 v4, v8, v9
	v_cvt_pk_bf16_f32 v5, v10, v11
	v_cvt_pk_bf16_f32 v6, v6, v7
	v_cvt_pk_bf16_f32 v7, v14, v15
	global_store_dwordx4 v[20:21], v[4:7], off offset:256
	s_cbranch_vccnz .LBB0_897
	s_andn2_b64 vcc, exec, s[46:47]
	s_cbranch_vccnz .LBB0_896
	s_barrier
	s_branch .LBB0_896

; __device__ __forceinline__ void unpack8(const u32x4 w, f32x4& v0, f32x4& v1) { v0 = (f32x4){bf_lo(w.x), bf_hi(w.x), bf_lo(w.y), bf_hi(w.y)}; v1 = (f32x4){bf_lo(w.z), bf_hi(w.z), bf_lo(w.w), bf_hi(w.w)}; }
; __device__ __forceinline__ void rms_row_from_bf16(const bf16_t* xrow, const float* g, bf16_t* obf, unsigned char* o8, float* of32, int lane) {
;     f32x4 v[16]; float s = 0.f;
; #pragma unroll
;     for (int j = 0; j < 8; ++j) { pg8::unpack8(*(const u32x4*)(xrow + (lane + 64 * j) * 8), v[2 * j], v[2 * j + 1]); }
; #pragma unroll
;     for (int j = 0; j < 16; ++j) s += (v[j].x * v[j].x + v[j].y * v[j].y) + (v[j].z * v[j].z + v[j].w * v[j].w);
; __global__ void __launch_bounds__(NWAVES * 64, 2) fwd(Args args) {
;     ...
;             for (int m = gw; m < MTOT; m += NGW) rms_row_from_bf16(hb + (size_t)(m >> 13) * ((size_t)MG * D * 2) + (size_t)(m & (MG - 1)) * D, TAB + TB_NORM2, N2 + (size_t)m * D, ws + WS_N2I8 + (size_t)m * D, nullptr, lane);
.LBB0_977:
	s_ashr_i32 s4, s0, 13
	s_ashr_i32 s5, s4, 31
	v_and_b32_e32 v12, 0x1fff000, v110
	s_lshl_b64 s[4:5], s[4:5], 27
	v_lshlrev_b32_e32 v12, 1, v12
	v_lshl_add_u64 v[42:43], v[8:9], 0, s[4:5]
	v_lshl_add_u64 v[42:43], v[42:43], 0, v[12:13]
	global_load_dwordx4 v[0:3], v[14:15], off offset:16
	global_load_dwordx4 v[4:7], v[14:15], off
	v_readfirstlane_b32 s4, v42
	v_readfirstlane_b32 s5, v43
	s_nop 4
	global_load_dwordx4 v[42:45], v111, s[4:5] nt
	global_load_dwordx4 v[46:49], v111, s[4:5] offset:1024 nt
	global_load_dwordx4 v[52:55], v111, s[4:5] offset:2048 nt
	global_load_dwordx4 v[56:59], v111, s[4:5] offset:3072 nt
	global_load_dwordx4 v[60:63], v112, s[4:5] nt
	global_load_dwordx4 v[68:71], v113, s[4:5] nt
	global_load_dwordx4 v[72:75], v114, s[4:5] nt
	global_load_dwordx4 v[84:87], v115, s[4:5] nt
	v_lshl_add_u64 v[40:41], v[10:11], 0, v[30:31]
	v_add_co_u32_e32 v50, vcc, s3, v40
	v_lshl_add_u64 v[38:39], v[10:11], 0, v[34:35]
	s_nop 0
	v_addc_co_u32_e32 v51, vcc, 0, v41, vcc
	v_add_co_u32_e32 v40, vcc, s8, v40
	s_add_i32 s0, s0, s1
	s_nop 0
	v_addc_co_u32_e32 v41, vcc, 0, v41, vcc
	v_add_u32_e32 v110, v110, v109
	v_lshl_add_u64 v[30:31], v[30:31], 0, v[32:33]
	v_lshl_add_u64 v[34:35], v[34:35], 0, v[36:37]
	s_cmpk_gt_i32 s0, 0x5fff
	s_waitcnt vmcnt(0)
	v_and_b32_e32 v89, 0xffff0000, v42
	v_and_b32_e32 v91, 0xffff0000, v43
	v_and_b32_e32 v121, 0xffff0000, v44
	v_and_b32_e32 v123, 0xffff0000, v45
	v_lshlrev_b32_e32 v88, 16, v42
	v_lshlrev_b32_e32 v90, 16, v43
	v_lshlrev_b32_e32 v120, 16, v44
	v_lshlrev_b32_e32 v122, 16, v45
	v_and_b32_e32 v125, 0xffff0000, v46
	v_and_b32_e32 v127, 0xffff0000, v47
	v_lshlrev_b32_e32 v94, 16, v62
	v_and_b32_e32 v95, 0xffff0000, v62
	v_lshlrev_b32_e32 v92, 16, v63
	v_and_b32_e32 v93, 0xffff0000, v63
	v_lshlrev_b32_e32 v66, 16, v68
	v_and_b32_e32 v67, 0xffff0000, v68
	v_lshlrev_b32_e32 v64, 16, v69
	v_and_b32_e32 v65, 0xffff0000, v69
	v_lshlrev_b32_e32 v62, 16, v70
	v_and_b32_e32 v63, 0xffff0000, v70
	v_mul_f32_e32 v12, v89, v89
	v_mul_f32_e32 v68, v91, v91
	v_mul_f32_e32 v69, v121, v121
	v_mul_f32_e32 v70, v123, v123
	v_lshlrev_b32_e32 v124, 16, v46
	v_lshlrev_b32_e32 v126, 16, v47
	v_and_b32_e32 v129, 0xffff0000, v48
	v_and_b32_e32 v131, 0xffff0000, v49
	v_lshlrev_b32_e32 v104, 16, v58
	v_and_b32_e32 v105, 0xffff0000, v58
	v_lshlrev_b32_e32 v106, 16, v59
	v_and_b32_e32 v107, 0xffff0000, v59
	v_lshlrev_b32_e32 v100, 16, v60
	v_and_b32_e32 v101, 0xffff0000, v60
	v_lshlrev_b32_e32 v98, 16, v61
	v_and_b32_e32 v99, 0xffff0000, v61
	v_lshlrev_b32_e32 v60, 16, v71
	v_and_b32_e32 v61, 0xffff0000, v71
	v_lshlrev_b32_e32 v58, 16, v72
	v_and_b32_e32 v59, 0xffff0000, v72
	v_mul_f32_e32 v71, v125, v125
	v_mul_f32_e32 v72, v127, v127
	v_fmac_f32_e32 v12, v88, v88
	v_fmac_f32_e32 v68, v90, v90
	v_fmac_f32_e32 v69, v120, v120
	v_fmac_f32_e32 v70, v122, v122
	v_lshlrev_b32_e32 v128, 16, v48
	v_lshlrev_b32_e32 v130, 16, v49
	v_and_b32_e32 v77, 0xffff0000, v52
	v_and_b32_e32 v79, 0xffff0000, v53
	v_lshlrev_b32_e32 v80, 16, v54
	v_and_b32_e32 v81, 0xffff0000, v54
	v_lshlrev_b32_e32 v82, 16, v55
	v_and_b32_e32 v83, 0xffff0000, v55
	v_lshlrev_b32_e32 v96, 16, v56
	v_and_b32_e32 v97, 0xffff0000, v56
	v_lshlrev_b32_e32 v102, 16, v57
	v_and_b32_e32 v103, 0xffff0000, v57
	v_lshlrev_b32_e32 v56, 16, v73
	v_and_b32_e32 v57, 0xffff0000, v73
	v_lshlrev_b32_e32 v54, 16, v74
	v_and_b32_e32 v55, 0xffff0000, v74
	v_mul_f32_e32 v73, v129, v129
	v_mul_f32_e32 v74, v131, v131
	v_fmac_f32_e32 v71, v124, v124
	v_fmac_f32_e32 v72, v126, v126
	v_add_f32_e32 v12, v12, v68
	v_add_f32_e32 v68, v69, v70
	v_lshlrev_b32_e32 v76, 16, v52
	v_lshlrev_b32_e32 v78, 16, v53
	v_lshlrev_b32_e32 v52, 16, v75
	v_and_b32_e32 v53, 0xffff0000, v75
	v_lshlrev_b32_e32 v42, 16, v84
	v_and_b32_e32 v43, 0xffff0000, v84
	v_mul_f32_e32 v75, v77, v77
	v_mul_f32_e32 v84, v79, v79
	v_fmac_f32_e32 v73, v128, v128
	v_fmac_f32_e32 v74, v130, v130
	v_add_f32_e32 v69, v71, v72
	v_add_f32_e32 v12, v12, v68
	v_lshlrev_b32_e32 v44, 16, v85
	v_and_b32_e32 v45, 0xffff0000, v85
	v_lshlrev_b32_e32 v46, 16, v86
	v_and_b32_e32 v47, 0xffff0000, v86
	v_mul_f32_e32 v85, v81, v81
	v_mul_f32_e32 v86, v83, v83
	v_fmac_f32_e32 v75, v76, v76
	v_fmac_f32_e32 v84, v78, v78
	v_add_f32_e32 v70, v73, v74
	v_add_f32_e32 v12, v12, v69
	v_lshlrev_b32_e32 v48, 16, v87
	v_and_b32_e32 v49, 0xffff0000, v87
	v_mul_f32_e32 v87, v97, v97
	v_mul_f32_e32 v119, v103, v103
	v_fmac_f32_e32 v85, v80, v80
	v_fmac_f32_e32 v86, v82, v82
	v_add_f32_e32 v71, v75, v84
	v_add_f32_e32 v12, v70, v12
	v_mul_f32_e32 v132, v105, v105
	v_mul_f32_e32 v133, v107, v107
	v_fmac_f32_e32 v87, v96, v96
	v_fmac_f32_e32 v119, v102, v102
	v_add_f32_e32 v72, v85, v86
	v_add_f32_e32 v12, v71, v12
	v_mul_f32_e32 v134, v101, v101
	v_mul_f32_e32 v135, v99, v99
	v_fmac_f32_e32 v132, v104, v104
	v_fmac_f32_e32 v133, v106, v106
	v_add_f32_e32 v73, v87, v119
	v_add_f32_e32 v12, v72, v12
	v_mul_f32_e32 v136, v95, v95
	v_mul_f32_e32 v137, v93, v93
	v_fmac_f32_e32 v134, v100, v100
	v_fmac_f32_e32 v135, v98, v98
	v_add_f32_e32 v74, v132, v133
	v_add_f32_e32 v12, v73, v12
	v_mul_f32_e32 v138, v67, v67
	v_mul_f32_e32 v139, v65, v65
	v_fmac_f32_e32 v136, v94, v94
	v_fmac_f32_e32 v137, v92, v92
	v_add_f32_e32 v75, v134, v135
	v_add_f32_e32 v12, v74, v12
	v_mul_f32_e32 v140, v63, v63
	v_mul_f32_e32 v141, v61, v61
	v_fmac_f32_e32 v138, v66, v66
	v_fmac_f32_e32 v139, v64, v64
	v_add_f32_e32 v84, v136, v137
	v_add_f32_e32 v12, v75, v12
	v_mul_f32_e32 v142, v59, v59
	v_mul_f32_e32 v143, v57, v57
	v_fmac_f32_e32 v140, v62, v62
	v_fmac_f32_e32 v141, v60, v60
	v_add_f32_e32 v85, v138, v139
	v_add_f32_e32 v12, v84, v12
	v_mul_f32_e32 v144, v55, v55
	v_mul_f32_e32 v145, v53, v53
	v_fmac_f32_e32 v142, v58, v58
	v_fmac_f32_e32 v143, v56, v56
	v_add_f32_e32 v86, v140, v141
	v_add_f32_e32 v12, v85, v12
	v_mul_f32_e32 v146, v43, v43
	v_mul_f32_e32 v147, v45, v45
	v_fmac_f32_e32 v144, v54, v54
	v_fmac_f32_e32 v145, v52, v52
	v_add_f32_e32 v87, v142, v143
	v_add_f32_e32 v12, v86, v12
	v_mul_f32_e32 v148, v47, v47
	v_mul_f32_e32 v149, v49, v49
	v_fmac_f32_e32 v146, v42, v42
	v_fmac_f32_e32 v147, v44, v44
	v_add_f32_e32 v119, v144, v145
	v_add_f32_e32 v12, v87, v12
	v_fmac_f32_e32 v148, v46, v46
	v_fmac_f32_e32 v149, v48, v48
	v_add_f32_e32 v132, v146, v147
	v_add_f32_e32 v12, v119, v12
	v_add_f32_e32 v133, v148, v149
	v_add_f32_e32 v12, v132, v12
	v_add_f32_e32 v12, v133, v12
	ds_swizzle_b32 v68, v12 offset:swizzle(SWAP,1)
	s_waitcnt lgkmcnt(0)
; __device__ __forceinline__ u32x4 pack8(const f32x4 v0, const f32x4 v1) { u32x4 w; w.x = cvt_pk_bf16(v0[0], v0[1]); w.y = cvt_pk_bf16(v0[2], v0[3]); w.z = cvt_pk_bf16(v1[0], v1[1]); w.w = cvt_pk_bf16(v1[2], v1[3]); return w; }
; __device__ __forceinline__ float wave_sum(float v) {
;     v += __builtin_bit_cast(float, __builtin_amdgcn_ds_swizzle(__builtin_bit_cast(int, v), (1 << 10) | 0x1f));
;     v += __builtin_bit_cast(float, __builtin_amdgcn_ds_swizzle(__builtin_bit_cast(int, v), (2 << 10) | 0x1f));
;     v += __builtin_bit_cast(float, __builtin_amdgcn_ds_swizzle(__builtin_bit_cast(int, v), (4 << 10) | 0x1f));
;     v += __builtin_bit_cast(float, __builtin_amdgcn_ds_swizzle(__builtin_bit_cast(int, v), (8 << 10) | 0x1f));
;     v += __builtin_bit_cast(float, __builtin_amdgcn_ds_swizzle(__builtin_bit_cast(int, v), (16 << 10) | 0x1f));
;     { const auto rr = __builtin_amdgcn_permlane32_swap(__float_as_uint(v), __float_as_uint(v), false, false); v = __uint_as_float(rr[0]) + __uint_as_float(rr[1]); }
; __device__ __forceinline__ void rms_row_from_bf16(const bf16_t* xrow, const float* g, bf16_t* obf, unsigned char* o8, float* of32, int lane) {
;     ...
;     const float rstd = 1.0f / sqrtf(wave_sum(s) * (1.f / D) + EPS);
; #pragma unroll
;     for (int j = 0; j < 8; ++j) { const int c = (lane + 64 * j) * 8; const f32x4 y0 = v[2 * j] * rstd * *(const f32x4*)(g + c), y1 = v[2 * j + 1] * rstd * *(const f32x4*)(g + c + 4);
;         if (obf) *(u32x4*)(obf + c) = pg8::pack8(y0, y1);
;         if (o8) *(u32x2*)(o8 + c) = (u32x2){pk4_i8(y0.x, y0.y, y0.z, y0.w, XN_QS), pk4_i8(y1.x, y1.y, y1.z, y1.w, XN_QS)};
;         if (of32) { *(f32x4*)(of32 + c) = y0; *(f32x4*)(of32 + c + 4) = y1; } }
	v_add_f32_e32 v12, v12, v68
	ds_swizzle_b32 v68, v12 offset:swizzle(SWAP,2)
	s_waitcnt lgkmcnt(0)
	v_add_f32_e32 v12, v12, v68
	ds_swizzle_b32 v68, v12 offset:swizzle(SWAP,4)
	s_waitcnt lgkmcnt(0)
	v_add_f32_e32 v12, v12, v68
	ds_swizzle_b32 v68, v12 offset:swizzle(SWAP,8)
	s_waitcnt lgkmcnt(0)
	v_add_f32_e32 v12, v12, v68
	ds_swizzle_b32 v68, v12 offset:swizzle(SWAP,16)
	s_waitcnt lgkmcnt(0)
	v_add_f32_e32 v12, v12, v68
	v_mov_b32_e32 v68, v12
	s_nop 1
	v_permlane32_swap_b32_e32 v12, v68
	v_add_f32_e32 v12, v12, v68
	v_fmamk_f32 v12, v12, 0x39800000, v116
	v_mul_f32_e32 v68, 0x4f800000, v12
	v_cmp_gt_f32_e32 vcc, s2, v12
	s_nop 1
	v_cndmask_b32_e32 v12, v12, v68, vcc
	v_sqrt_f32_e32 v68, v12
	s_nop 0
	v_add_u32_e32 v69, -1, v68
	v_add_u32_e32 v70, 1, v68
	v_fma_f32 v71, -v69, v68, v12
	v_fma_f32 v72, -v70, v68, v12
	v_cmp_ge_f32_e64 s[36:37], 0, v71
	s_nop 1
	v_cndmask_b32_e64 v68, v68, v69, s[36:37]
	v_cmp_lt_f32_e64 s[36:37], 0, v72
	s_nop 1
	v_cndmask_b32_e64 v68, v68, v70, s[36:37]
	v_mul_f32_e32 v69, 0x37800000, v68
	v_cndmask_b32_e32 v68, v68, v69, vcc
	v_cmp_class_f32_e32 vcc, v12, v117
	s_nop 1
	v_cndmask_b32_e32 v12, v68, v12, vcc
	v_div_scale_f32 v68, s[4:5], v12, v12, 1.0
	v_rcp_f32_e32 v70, v68
	v_div_scale_f32 v69, vcc, 1.0, v12, 1.0
	v_fma_f32 v71, -v68, v70, 1.0
	v_fmac_f32_e32 v70, v71, v70
	v_mul_f32_e32 v71, v69, v70
	v_fma_f32 v72, -v68, v71, v69
	v_fmac_f32_e32 v71, v72, v70
	v_fma_f32 v68, -v68, v71, v69
	v_div_fmas_f32 v68, v68, v70, v71
	v_div_fixup_f32 v12, v68, v12, 1.0
	v_pk_mul_f32 v[84:85], v[12:13], v[88:89] op_sel_hi:[0,1]
	v_pk_mul_f32 v[88:89], v[12:13], v[90:91] op_sel_hi:[0,1]
	v_pk_mul_f32 v[86:87], v[12:13], v[120:121] op_sel_hi:[0,1]
	v_pk_mul_f32 v[90:91], v[12:13], v[122:123] op_sel_hi:[0,1]
	v_pk_mul_f32 v[6:7], v[6:7], v[88:89]
	v_pk_mul_f32 v[4:5], v[4:5], v[84:85]
	v_pk_mul_f32 v[86:87], v[0:1], v[86:87]
	v_pk_mul_f32 v[84:85], v[2:3], v[90:91]
	v_cvt_pk_bf16_f32 v0, v4, v5
	v_cvt_pk_bf16_f32 v1, v6, v7
	v_cvt_pk_bf16_f32 v2, v86, v87
	v_mul_f32_e32 v4, 0x41fe0000, v4
	v_cvt_pk_bf16_f32 v3, v84, v85
	v_mul_f32_e32 v5, 0x41fe0000, v5
	v_mul_f32_e32 v7, 0x41fe0000, v7
	v_mul_f32_e32 v87, 0x41fe0000, v87
	v_mul_f32_e32 v6, 0x41fe0000, v6
	v_mul_f32_e32 v86, 0x41fe0000, v86
	v_mul_f32_e32 v84, 0x41fe0000, v84
	v_mul_f32_e32 v85, 0x41fe0000, v85
	global_store_dwordx4 v[40:41], v[0:3], off offset:-4096
	v_pk_mul_f32 v[68:69], v[12:13], v[124:125] op_sel_hi:[0,1]
	v_pk_mul_f32 v[70:71], v[12:13], v[126:127] op_sel_hi:[0,1]
	v_med3_f32 v0, v4, s6, v118
	v_med3_f32 v1, v5, s6, v118
	v_med3_f32 v3, v7, s6, v118
	v_med3_f32 v5, v87, s6, v118
	v_med3_f32 v2, v6, s6, v118
	v_med3_f32 v4, v86, s6, v118
	v_med3_f32 v6, v84, s6, v118
	v_med3_f32 v7, v85, s6, v118
	v_rndne_f32_e32 v0, v0
	v_rndne_f32_e32 v1, v1
	v_rndne_f32_e32 v3, v3
	v_rndne_f32_e32 v5, v5
	v_rndne_f32_e32 v2, v2
	v_rndne_f32_e32 v4, v4
	v_rndne_f32_e32 v6, v6
	v_rndne_f32_e32 v7, v7
	v_cvt_i32_f32_e32 v0, v0
	v_cvt_i32_f32_e32 v1, v1
	v_cvt_i32_f32_e32 v3, v3
	v_cvt_i32_f32_e32 v5, v5
	v_cvt_i32_f32_sdwa v2, v2 dst_sel:WORD_1 dst_unused:UNUSED_PAD src0_sel:DWORD
	v_cvt_i32_f32_e32 v4, v4
	v_cvt_i32_f32_sdwa v6, v6 dst_sel:WORD_1 dst_unused:UNUSED_PAD src0_sel:DWORD
	v_cvt_i32_f32_e32 v7, v7
	v_lshlrev_b32_e32 v1, 8, v1
	v_perm_b32 v0, v3, v0, s7
	v_lshlrev_b32_e32 v3, 8, v5
	v_and_b32_e32 v2, 0xff0000, v2
	v_and_b32_e32 v5, 0xff0000, v6
	v_perm_b32 v4, v7, v4, s7
	v_and_b32_e32 v1, 0xff00, v1
	v_and_b32_e32 v3, 0xff00, v3
	v_or3_b32 v0, v0, v1, v2
	v_or3_b32 v1, v4, v3, v5
	global_store_dwordx2 v[38:39], v[0:1], off offset:-2048
	global_load_dwordx4 v[0:3], v[16:17], off
	s_nop 0
	global_load_dwordx4 v[4:7], v[16:17], off offset:16
	v_pk_mul_f32 v[72:73], v[12:13], v[128:129] op_sel_hi:[0,1]
	v_pk_mul_f32 v[74:75], v[12:13], v[130:131] op_sel_hi:[0,1]
	v_pk_mul_f32 v[76:77], v[12:13], v[76:77] op_sel_hi:[0,1]
	v_pk_mul_f32 v[78:79], v[12:13], v[78:79] op_sel_hi:[0,1]
	v_pk_mul_f32 v[80:81], v[12:13], v[80:81] op_sel_hi:[0,1]
	v_pk_mul_f32 v[82:83], v[12:13], v[82:83] op_sel_hi:[0,1]
	v_pk_mul_f32 v[96:97], v[12:13], v[96:97] op_sel_hi:[0,1]
	v_pk_mul_f32 v[102:103], v[12:13], v[102:103] op_sel_hi:[0,1]
	v_pk_mul_f32 v[104:105], v[12:13], v[104:105] op_sel_hi:[0,1]
	v_pk_mul_f32 v[106:107], v[12:13], v[106:107] op_sel_hi:[0,1]
	v_pk_mul_f32 v[100:101], v[12:13], v[100:101] op_sel_hi:[0,1]
	v_pk_mul_f32 v[98:99], v[12:13], v[98:99] op_sel_hi:[0,1]
	v_pk_mul_f32 v[94:95], v[12:13], v[94:95] op_sel_hi:[0,1]
	v_pk_mul_f32 v[92:93], v[12:13], v[92:93] op_sel_hi:[0,1]
	v_pk_mul_f32 v[66:67], v[12:13], v[66:67] op_sel_hi:[0,1]
	v_pk_mul_f32 v[64:65], v[12:13], v[64:65] op_sel_hi:[0,1]
	v_pk_mul_f32 v[62:63], v[12:13], v[62:63] op_sel_hi:[0,1]
	v_pk_mul_f32 v[60:61], v[12:13], v[60:61] op_sel_hi:[0,1]
	v_pk_mul_f32 v[58:59], v[12:13], v[58:59] op_sel_hi:[0,1]
	v_pk_mul_f32 v[56:57], v[12:13], v[56:57] op_sel_hi:[0,1]
	v_pk_mul_f32 v[54:55], v[12:13], v[54:55] op_sel_hi:[0,1]
	v_pk_mul_f32 v[52:53], v[12:13], v[52:53] op_sel_hi:[0,1]
	v_pk_mul_f32 v[42:43], v[12:13], v[42:43] op_sel_hi:[0,1]
	v_pk_mul_f32 v[44:45], v[12:13], v[44:45] op_sel_hi:[0,1]
	v_pk_mul_f32 v[46:47], v[12:13], v[46:47] op_sel_hi:[0,1]
	v_pk_mul_f32 v[48:49], v[12:13], v[48:49] op_sel_hi:[0,1]
	s_waitcnt vmcnt(1)
	v_pk_mul_f32 v[70:71], v[2:3], v[70:71]
	v_pk_mul_f32 v[68:69], v[0:1], v[68:69]
	s_waitcnt vmcnt(0)
; __device__ __forceinline__ u32x4 pack8(const f32x4 v0, const f32x4 v1) { u32x4 w; w.x = cvt_pk_bf16(v0[0], v0[1]); w.y = cvt_pk_bf16(v0[2], v0[3]); w.z = cvt_pk_bf16(v1[0], v1[1]); w.w = cvt_pk_bf16(v1[2], v1[3]); return w; }
; __device__ __forceinline__ void rms_row_from_bf16(const bf16_t* xrow, const float* g, bf16_t* obf, unsigned char* o8, float* of32, int lane) {
;     ...
; #pragma unroll
;     for (int j = 0; j < 8; ++j) { const int c = (lane + 64 * j) * 8; const f32x4 y0 = v[2 * j] * rstd * *(const f32x4*)(g + c), y1 = v[2 * j + 1] * rstd * *(const f32x4*)(g + c + 4);
;         if (obf) *(u32x4*)(obf + c) = pg8::pack8(y0, y1);
;         if (o8) *(u32x2*)(o8 + c) = (u32x2){pk4_i8(y0.x, y0.y, y0.z, y0.w, XN_QS), pk4_i8(y1.x, y1.y, y1.z, y1.w, XN_QS)};
;         if (of32) { *(f32x4*)(of32 + c) = y0; *(f32x4*)(of32 + c + 4) = y1; } }
	v_pk_mul_f32 v[4:5], v[72:73], v[4:5]
	v_pk_mul_f32 v[6:7], v[74:75], v[6:7]
	v_cvt_pk_bf16_f32 v0, v68, v69
	v_cvt_pk_bf16_f32 v1, v70, v71
	v_cvt_pk_bf16_f32 v2, v4, v5
	v_mul_f32_e32 v68, 0x41fe0000, v68
	v_cvt_pk_bf16_f32 v3, v6, v7
	v_mul_f32_e32 v69, 0x41fe0000, v69
	v_mul_f32_e32 v71, 0x41fe0000, v71
	v_mul_f32_e32 v5, 0x41fe0000, v5
	v_mul_f32_e32 v70, 0x41fe0000, v70
	v_mul_f32_e32 v4, 0x41fe0000, v4
	v_mul_f32_e32 v6, 0x41fe0000, v6
	v_mul_f32_e32 v7, 0x41fe0000, v7
	global_store_dwordx4 v[50:51], v[0:3], off offset:1024
	v_med3_f32 v5, v5, s6, v118
	v_med3_f32 v4, v4, s6, v118
	v_med3_f32 v0, v68, s6, v118
	v_med3_f32 v1, v69, s6, v118
	v_med3_f32 v3, v71, s6, v118
	v_med3_f32 v2, v70, s6, v118
	v_med3_f32 v6, v6, s6, v118
	v_med3_f32 v7, v7, s6, v118
	v_rndne_f32_e32 v0, v0
	v_rndne_f32_e32 v1, v1
	v_rndne_f32_e32 v3, v3
	v_rndne_f32_e32 v5, v5
	v_rndne_f32_e32 v2, v2
	v_rndne_f32_e32 v4, v4
	v_rndne_f32_e32 v6, v6
	v_rndne_f32_e32 v7, v7
	v_cvt_i32_f32_e32 v0, v0
	v_cvt_i32_f32_e32 v1, v1
	v_cvt_i32_f32_e32 v3, v3
	v_cvt_i32_f32_e32 v5, v5
	v_cvt_i32_f32_sdwa v2, v2 dst_sel:WORD_1 dst_unused:UNUSED_PAD src0_sel:DWORD
	v_cvt_i32_f32_e32 v4, v4
	v_cvt_i32_f32_sdwa v6, v6 dst_sel:WORD_1 dst_unused:UNUSED_PAD src0_sel:DWORD
	v_cvt_i32_f32_e32 v7, v7
	v_lshlrev_b32_e32 v1, 8, v1
	v_perm_b32 v0, v3, v0, s7
	v_lshlrev_b32_e32 v3, 8, v5
	v_and_b32_e32 v2, 0xff0000, v2
	v_and_b32_e32 v5, 0xff0000, v6
	v_perm_b32 v4, v7, v4, s7
	v_and_b32_e32 v1, 0xff00, v1
	v_and_b32_e32 v3, 0xff00, v3
	v_or3_b32 v0, v0, v1, v2
	v_or3_b32 v1, v4, v3, v5
	global_store_dwordx2 v[38:39], v[0:1], off offset:-1536
	global_load_dwordx4 v[0:3], v[18:19], off
	s_nop 0
	global_load_dwordx4 v[4:7], v[18:19], off offset:16
	s_waitcnt vmcnt(1)
	v_pk_mul_f32 v[68:69], v[78:79], v[2:3]
	v_pk_mul_f32 v[70:71], v[76:77], v[0:1]
	s_waitcnt vmcnt(0)
	v_pk_mul_f32 v[4:5], v[80:81], v[4:5]
	v_pk_mul_f32 v[6:7], v[82:83], v[6:7]
	v_cvt_pk_bf16_f32 v0, v70, v71
	v_cvt_pk_bf16_f32 v1, v68, v69
	v_cvt_pk_bf16_f32 v2, v4, v5
	v_mul_f32_e32 v70, 0x41fe0000, v70
	v_cvt_pk_bf16_f32 v3, v6, v7
	v_mul_f32_e32 v71, 0x41fe0000, v71
	v_mul_f32_e32 v69, 0x41fe0000, v69
	v_mul_f32_e32 v5, 0x41fe0000, v5
	v_mul_f32_e32 v68, 0x41fe0000, v68
	v_mul_f32_e32 v4, 0x41fe0000, v4
	v_mul_f32_e32 v6, 0x41fe0000, v6
	v_mul_f32_e32 v7, 0x41fe0000, v7
	global_store_dwordx4 v[50:51], v[0:3], off offset:2048
	v_med3_f32 v5, v5, s6, v118
	v_med3_f32 v4, v4, s6, v118
	v_med3_f32 v0, v70, s6, v118
	v_med3_f32 v1, v71, s6, v118
	v_med3_f32 v3, v69, s6, v118
	v_med3_f32 v2, v68, s6, v118
	v_med3_f32 v6, v6, s6, v118
	v_med3_f32 v7, v7, s6, v118
	v_rndne_f32_e32 v0, v0
	v_rndne_f32_e32 v1, v1
	v_rndne_f32_e32 v3, v3
	v_rndne_f32_e32 v5, v5
	v_rndne_f32_e32 v2, v2
	v_rndne_f32_e32 v4, v4
	v_rndne_f32_e32 v6, v6
	v_rndne_f32_e32 v7, v7
	v_cvt_i32_f32_e32 v0, v0
	v_cvt_i32_f32_e32 v1, v1
	v_cvt_i32_f32_e32 v3, v3
	v_cvt_i32_f32_e32 v5, v5
	v_cvt_i32_f32_sdwa v2, v2 dst_sel:WORD_1 dst_unused:UNUSED_PAD src0_sel:DWORD
	v_cvt_i32_f32_e32 v4, v4
	v_cvt_i32_f32_sdwa v6, v6 dst_sel:WORD_1 dst_unused:UNUSED_PAD src0_sel:DWORD
	v_cvt_i32_f32_e32 v7, v7
	v_lshlrev_b32_e32 v1, 8, v1
	v_perm_b32 v0, v3, v0, s7
	v_lshlrev_b32_e32 v3, 8, v5
	v_and_b32_e32 v2, 0xff0000, v2
	v_and_b32_e32 v5, 0xff0000, v6
	v_perm_b32 v4, v7, v4, s7
	v_and_b32_e32 v1, 0xff00, v1
	v_and_b32_e32 v3, 0xff00, v3
	v_or3_b32 v0, v0, v1, v2
	v_or3_b32 v1, v4, v3, v5
	global_store_dwordx2 v[38:39], v[0:1], off offset:-1024
	global_load_dwordx4 v[0:3], v[20:21], off
	s_nop 0
	global_load_dwordx4 v[4:7], v[20:21], off offset:16
	s_waitcnt vmcnt(1)
	v_pk_mul_f32 v[68:69], v[102:103], v[2:3]
	v_pk_mul_f32 v[70:71], v[96:97], v[0:1]
	s_waitcnt vmcnt(0)
	v_pk_mul_f32 v[4:5], v[104:105], v[4:5]
	v_pk_mul_f32 v[6:7], v[106:107], v[6:7]
	v_cvt_pk_bf16_f32 v0, v70, v71
	v_cvt_pk_bf16_f32 v1, v68, v69
	v_cvt_pk_bf16_f32 v2, v4, v5
	v_mul_f32_e32 v70, 0x41fe0000, v70
	v_cvt_pk_bf16_f32 v3, v6, v7
	v_mul_f32_e32 v71, 0x41fe0000, v71
	v_mul_f32_e32 v69, 0x41fe0000, v69
	v_mul_f32_e32 v5, 0x41fe0000, v5
	v_mul_f32_e32 v68, 0x41fe0000, v68
	v_mul_f32_e32 v4, 0x41fe0000, v4
	v_mul_f32_e32 v6, 0x41fe0000, v6
	v_mul_f32_e32 v7, 0x41fe0000, v7
	global_store_dwordx4 v[50:51], v[0:3], off offset:3072
	v_med3_f32 v5, v5, s6, v118
	v_med3_f32 v4, v4, s6, v118
	v_med3_f32 v0, v70, s6, v118
	v_med3_f32 v1, v71, s6, v118
	v_med3_f32 v3, v69, s6, v118
	v_med3_f32 v2, v68, s6, v118
	v_med3_f32 v6, v6, s6, v118
	v_med3_f32 v7, v7, s6, v118
	v_rndne_f32_e32 v0, v0
	v_rndne_f32_e32 v1, v1
	v_rndne_f32_e32 v3, v3
	v_rndne_f32_e32 v5, v5
	v_rndne_f32_e32 v2, v2
	v_rndne_f32_e32 v4, v4
	v_rndne_f32_e32 v6, v6
	v_rndne_f32_e32 v7, v7
	v_cvt_i32_f32_e32 v0, v0
	v_cvt_i32_f32_e32 v1, v1
	v_cvt_i32_f32_e32 v3, v3
	v_cvt_i32_f32_e32 v5, v5
	v_cvt_i32_f32_sdwa v2, v2 dst_sel:WORD_1 dst_unused:UNUSED_PAD src0_sel:DWORD
	v_cvt_i32_f32_e32 v4, v4
	v_cvt_i32_f32_sdwa v6, v6 dst_sel:WORD_1 dst_unused:UNUSED_PAD src0_sel:DWORD
	v_cvt_i32_f32_e32 v7, v7
	v_lshlrev_b32_e32 v1, 8, v1
	v_perm_b32 v0, v3, v0, s7
	v_lshlrev_b32_e32 v3, 8, v5
	v_and_b32_e32 v2, 0xff0000, v2
	v_and_b32_e32 v5, 0xff0000, v6
	v_perm_b32 v4, v7, v4, s7
	v_and_b32_e32 v1, 0xff00, v1
	v_and_b32_e32 v3, 0xff00, v3
	v_or3_b32 v0, v0, v1, v2
	v_or3_b32 v1, v4, v3, v5
	global_store_dwordx2 v[38:39], v[0:1], off offset:-512
	global_load_dwordx4 v[0:3], v[22:23], off
	s_nop 0
	global_load_dwordx4 v[4:7], v[22:23], off offset:16
	s_waitcnt vmcnt(1)
	v_pk_mul_f32 v[50:51], v[98:99], v[2:3]
	v_pk_mul_f32 v[68:69], v[100:101], v[0:1]
	s_waitcnt vmcnt(0)
; __device__ __forceinline__ u32x4 pack8(const f32x4 v0, const f32x4 v1) { u32x4 w; w.x = cvt_pk_bf16(v0[0], v0[1]); w.y = cvt_pk_bf16(v0[2], v0[3]); w.z = cvt_pk_bf16(v1[0], v1[1]); w.w = cvt_pk_bf16(v1[2], v1[3]); return w; }
; __device__ __forceinline__ void rms_row_from_bf16(const bf16_t* xrow, const float* g, bf16_t* obf, unsigned char* o8, float* of32, int lane) {
;     ...
; #pragma unroll
;     for (int j = 0; j < 8; ++j) { const int c = (lane + 64 * j) * 8; const f32x4 y0 = v[2 * j] * rstd * *(const f32x4*)(g + c), y1 = v[2 * j + 1] * rstd * *(const f32x4*)(g + c + 4);
;         if (obf) *(u32x4*)(obf + c) = pg8::pack8(y0, y1);
;         if (o8) *(u32x2*)(o8 + c) = (u32x2){pk4_i8(y0.x, y0.y, y0.z, y0.w, XN_QS), pk4_i8(y1.x, y1.y, y1.z, y1.w, XN_QS)};
;         if (of32) { *(f32x4*)(of32 + c) = y0; *(f32x4*)(of32 + c + 4) = y1; } }
	v_pk_mul_f32 v[4:5], v[94:95], v[4:5]
	v_pk_mul_f32 v[6:7], v[92:93], v[6:7]
	v_cvt_pk_bf16_f32 v0, v68, v69
	v_cvt_pk_bf16_f32 v1, v50, v51
	v_cvt_pk_bf16_f32 v2, v4, v5
	v_mul_f32_e32 v68, 0x41fe0000, v68
	v_cvt_pk_bf16_f32 v3, v6, v7
	v_mul_f32_e32 v69, 0x41fe0000, v69
	v_mul_f32_e32 v51, 0x41fe0000, v51
	v_mul_f32_e32 v5, 0x41fe0000, v5
	v_mul_f32_e32 v50, 0x41fe0000, v50
	v_mul_f32_e32 v4, 0x41fe0000, v4
	v_mul_f32_e32 v6, 0x41fe0000, v6
	v_mul_f32_e32 v7, 0x41fe0000, v7
	global_store_dwordx4 v[40:41], v[0:3], off
	v_med3_f32 v5, v5, s6, v118
	v_med3_f32 v4, v4, s6, v118
	v_med3_f32 v0, v68, s6, v118
	v_med3_f32 v1, v69, s6, v118
	v_med3_f32 v3, v51, s6, v118
	v_med3_f32 v2, v50, s6, v118
	v_med3_f32 v6, v6, s6, v118
	v_med3_f32 v7, v7, s6, v118
	v_rndne_f32_e32 v0, v0
	v_rndne_f32_e32 v1, v1
	v_rndne_f32_e32 v3, v3
	v_rndne_f32_e32 v5, v5
	v_rndne_f32_e32 v2, v2
	v_rndne_f32_e32 v4, v4
	v_rndne_f32_e32 v6, v6
	v_rndne_f32_e32 v7, v7
	v_cvt_i32_f32_e32 v0, v0
	v_cvt_i32_f32_e32 v1, v1
	v_cvt_i32_f32_e32 v3, v3
	v_cvt_i32_f32_e32 v5, v5
	v_cvt_i32_f32_sdwa v2, v2 dst_sel:WORD_1 dst_unused:UNUSED_PAD src0_sel:DWORD
	v_cvt_i32_f32_e32 v4, v4
	v_cvt_i32_f32_sdwa v6, v6 dst_sel:WORD_1 dst_unused:UNUSED_PAD src0_sel:DWORD
	v_cvt_i32_f32_e32 v7, v7
	v_lshlrev_b32_e32 v1, 8, v1
	v_perm_b32 v0, v3, v0, s7
	v_lshlrev_b32_e32 v3, 8, v5
	v_and_b32_e32 v2, 0xff0000, v2
	v_and_b32_e32 v5, 0xff0000, v6
	v_perm_b32 v4, v7, v4, s7
	v_and_b32_e32 v1, 0xff00, v1
	v_and_b32_e32 v3, 0xff00, v3
	v_or3_b32 v0, v0, v1, v2
	v_or3_b32 v1, v4, v3, v5
	global_store_dwordx2 v[38:39], v[0:1], off
	global_load_dwordx4 v[0:3], v[24:25], off
	s_nop 0
	global_load_dwordx4 v[4:7], v[24:25], off offset:16
	s_waitcnt vmcnt(1)
	v_pk_mul_f32 v[50:51], v[64:65], v[2:3]
	v_pk_mul_f32 v[64:65], v[66:67], v[0:1]
	s_waitcnt vmcnt(0)
	v_pk_mul_f32 v[4:5], v[62:63], v[4:5]
	v_pk_mul_f32 v[6:7], v[60:61], v[6:7]
	v_cvt_pk_bf16_f32 v0, v64, v65
	v_cvt_pk_bf16_f32 v1, v50, v51
	v_cvt_pk_bf16_f32 v2, v4, v5
	v_mul_f32_e32 v60, 0x41fe0000, v64
	v_cvt_pk_bf16_f32 v3, v6, v7
	v_mul_f32_e32 v61, 0x41fe0000, v65
	v_mul_f32_e32 v51, 0x41fe0000, v51
	v_mul_f32_e32 v5, 0x41fe0000, v5
	v_mul_f32_e32 v50, 0x41fe0000, v50
	v_mul_f32_e32 v4, 0x41fe0000, v4
	v_mul_f32_e32 v6, 0x41fe0000, v6
	v_mul_f32_e32 v7, 0x41fe0000, v7
	global_store_dwordx4 v[40:41], v[0:3], off offset:1024
	v_med3_f32 v5, v5, s6, v118
	v_med3_f32 v4, v4, s6, v118
	v_med3_f32 v0, v60, s6, v118
	v_med3_f32 v1, v61, s6, v118
	v_med3_f32 v3, v51, s6, v118
	v_med3_f32 v2, v50, s6, v118
	v_med3_f32 v6, v6, s6, v118
	v_med3_f32 v7, v7, s6, v118
	v_rndne_f32_e32 v0, v0
	v_rndne_f32_e32 v1, v1
	v_rndne_f32_e32 v3, v3
	v_rndne_f32_e32 v5, v5
	v_rndne_f32_e32 v2, v2
	v_rndne_f32_e32 v4, v4
	v_rndne_f32_e32 v6, v6
	v_rndne_f32_e32 v7, v7
	v_cvt_i32_f32_e32 v0, v0
	v_cvt_i32_f32_e32 v1, v1
	v_cvt_i32_f32_e32 v3, v3
	v_cvt_i32_f32_e32 v5, v5
	v_cvt_i32_f32_sdwa v2, v2 dst_sel:WORD_1 dst_unused:UNUSED_PAD src0_sel:DWORD
	v_cvt_i32_f32_e32 v4, v4
	v_cvt_i32_f32_sdwa v6, v6 dst_sel:WORD_1 dst_unused:UNUSED_PAD src0_sel:DWORD
	v_cvt_i32_f32_e32 v7, v7
	v_lshlrev_b32_e32 v1, 8, v1
	v_perm_b32 v0, v3, v0, s7
	v_lshlrev_b32_e32 v3, 8, v5
	v_and_b32_e32 v2, 0xff0000, v2
	v_and_b32_e32 v5, 0xff0000, v6
	v_perm_b32 v4, v7, v4, s7
	v_and_b32_e32 v1, 0xff00, v1
	v_and_b32_e32 v3, 0xff00, v3
	v_or3_b32 v0, v0, v1, v2
	v_or3_b32 v1, v4, v3, v5
	global_store_dwordx2 v[38:39], v[0:1], off offset:512
	global_load_dwordx4 v[0:3], v[26:27], off
	s_nop 0
	global_load_dwordx4 v[4:7], v[26:27], off offset:16
	s_waitcnt vmcnt(1)
; __device__ __forceinline__ u32x4 pack8(const f32x4 v0, const f32x4 v1) { u32x4 w; w.x = cvt_pk_bf16(v0[0], v0[1]); w.y = cvt_pk_bf16(v0[2], v0[3]); w.z = cvt_pk_bf16(v1[0], v1[1]); w.w = cvt_pk_bf16(v1[2], v1[3]); return w; }
; __device__ __forceinline__ void rms_row_from_bf16(const bf16_t* xrow, const float* g, bf16_t* obf, unsigned char* o8, float* of32, int lane) {
;     ...
; #pragma unroll
;     for (int j = 0; j < 8; ++j) { const int c = (lane + 64 * j) * 8; const f32x4 y0 = v[2 * j] * rstd * *(const f32x4*)(g + c), y1 = v[2 * j + 1] * rstd * *(const f32x4*)(g + c + 4);
;         if (obf) *(u32x4*)(obf + c) = pg8::pack8(y0, y1);
;         if (o8) *(u32x2*)(o8 + c) = (u32x2){pk4_i8(y0.x, y0.y, y0.z, y0.w, XN_QS), pk4_i8(y1.x, y1.y, y1.z, y1.w, XN_QS)};
;         if (of32) { *(f32x4*)(of32 + c) = y0; *(f32x4*)(of32 + c + 4) = y1; } }
	v_pk_mul_f32 v[50:51], v[56:57], v[2:3]
	v_pk_mul_f32 v[56:57], v[58:59], v[0:1]
	s_waitcnt vmcnt(0)
	v_pk_mul_f32 v[4:5], v[54:55], v[4:5]
	v_pk_mul_f32 v[6:7], v[52:53], v[6:7]
	v_cvt_pk_bf16_f32 v0, v56, v57
	v_cvt_pk_bf16_f32 v1, v50, v51
	v_cvt_pk_bf16_f32 v2, v4, v5
	v_mul_f32_e32 v52, 0x41fe0000, v56
	v_cvt_pk_bf16_f32 v3, v6, v7
	v_mul_f32_e32 v53, 0x41fe0000, v57
	v_mul_f32_e32 v51, 0x41fe0000, v51
	v_mul_f32_e32 v5, 0x41fe0000, v5
	v_mul_f32_e32 v50, 0x41fe0000, v50
	v_mul_f32_e32 v4, 0x41fe0000, v4
	v_mul_f32_e32 v6, 0x41fe0000, v6
	v_mul_f32_e32 v7, 0x41fe0000, v7
	global_store_dwordx4 v[40:41], v[0:3], off offset:2048
	v_med3_f32 v5, v5, s6, v118
	v_med3_f32 v4, v4, s6, v118
	v_med3_f32 v0, v52, s6, v118
	v_med3_f32 v1, v53, s6, v118
	v_med3_f32 v3, v51, s6, v118
	v_med3_f32 v2, v50, s6, v118
	v_med3_f32 v6, v6, s6, v118
	v_med3_f32 v7, v7, s6, v118
	v_rndne_f32_e32 v0, v0
	v_rndne_f32_e32 v1, v1
	v_rndne_f32_e32 v3, v3
	v_rndne_f32_e32 v5, v5
	v_rndne_f32_e32 v2, v2
	v_rndne_f32_e32 v4, v4
	v_rndne_f32_e32 v6, v6
	v_rndne_f32_e32 v7, v7
	v_cvt_i32_f32_e32 v0, v0
	v_cvt_i32_f32_e32 v1, v1
	v_cvt_i32_f32_e32 v3, v3
	v_cvt_i32_f32_e32 v5, v5
	v_cvt_i32_f32_sdwa v2, v2 dst_sel:WORD_1 dst_unused:UNUSED_PAD src0_sel:DWORD
	v_cvt_i32_f32_e32 v4, v4
	v_cvt_i32_f32_sdwa v6, v6 dst_sel:WORD_1 dst_unused:UNUSED_PAD src0_sel:DWORD
	v_cvt_i32_f32_e32 v7, v7
	v_lshlrev_b32_e32 v1, 8, v1
	v_perm_b32 v0, v3, v0, s7
	v_lshlrev_b32_e32 v3, 8, v5
	v_and_b32_e32 v2, 0xff0000, v2
	v_and_b32_e32 v5, 0xff0000, v6
	v_perm_b32 v4, v7, v4, s7
	v_and_b32_e32 v1, 0xff00, v1
	v_and_b32_e32 v3, 0xff00, v3
	v_or3_b32 v0, v0, v1, v2
	v_or3_b32 v1, v4, v3, v5
	global_store_dwordx2 v[38:39], v[0:1], off offset:1024
	global_load_dwordx4 v[0:3], v[28:29], off
	s_nop 0
	global_load_dwordx4 v[4:7], v[28:29], off offset:16
	s_waitcnt vmcnt(1)
	v_pk_mul_f32 v[44:45], v[44:45], v[2:3]
	v_pk_mul_f32 v[42:43], v[42:43], v[0:1]
	s_waitcnt vmcnt(0)
	v_pk_mul_f32 v[4:5], v[46:47], v[4:5]
	v_pk_mul_f32 v[6:7], v[48:49], v[6:7]
	v_cvt_pk_bf16_f32 v0, v42, v43
	v_cvt_pk_bf16_f32 v1, v44, v45
	v_cvt_pk_bf16_f32 v2, v4, v5
	v_mul_f32_e32 v12, 0x41fe0000, v42
	v_cvt_pk_bf16_f32 v3, v6, v7
	v_mul_f32_e32 v42, 0x41fe0000, v43
	v_mul_f32_e32 v43, 0x41fe0000, v44
	v_mul_f32_e32 v44, 0x41fe0000, v45
	v_mul_f32_e32 v5, 0x41fe0000, v5
	v_mul_f32_e32 v4, 0x41fe0000, v4
	v_mul_f32_e32 v6, 0x41fe0000, v6
	v_mul_f32_e32 v7, 0x41fe0000, v7
	global_store_dwordx4 v[40:41], v[0:3], off offset:3072
	v_med3_f32 v5, v5, s6, v118
	v_med3_f32 v4, v4, s6, v118
	v_med3_f32 v0, v12, s6, v118
	v_med3_f32 v1, v42, s6, v118
	v_med3_f32 v3, v44, s6, v118
	v_med3_f32 v2, v43, s6, v118
	v_med3_f32 v6, v6, s6, v118
	v_med3_f32 v7, v7, s6, v118
	v_rndne_f32_e32 v0, v0
	v_rndne_f32_e32 v1, v1
	v_rndne_f32_e32 v3, v3
	v_rndne_f32_e32 v5, v5
	v_rndne_f32_e32 v2, v2
	v_rndne_f32_e32 v4, v4
	v_rndne_f32_e32 v6, v6
	v_rndne_f32_e32 v7, v7
	v_cvt_i32_f32_e32 v0, v0
	v_cvt_i32_f32_e32 v1, v1
	v_cvt_i32_f32_e32 v3, v3
	v_cvt_i32_f32_e32 v5, v5
	v_cvt_i32_f32_sdwa v2, v2 dst_sel:WORD_1 dst_unused:UNUSED_PAD src0_sel:DWORD
	v_cvt_i32_f32_e32 v4, v4
	v_cvt_i32_f32_sdwa v6, v6 dst_sel:WORD_1 dst_unused:UNUSED_PAD src0_sel:DWORD
	v_cvt_i32_f32_e32 v7, v7
	v_lshlrev_b32_e32 v1, 8, v1
	v_perm_b32 v0, v3, v0, s7
	v_lshlrev_b32_e32 v3, 8, v5
	v_and_b32_e32 v2, 0xff0000, v2
	v_and_b32_e32 v5, 0xff0000, v6
	v_perm_b32 v4, v7, v4, s7
	v_and_b32_e32 v1, 0xff00, v1
	v_and_b32_e32 v3, 0xff00, v3
	v_or3_b32 v0, v0, v1, v2
	v_or3_b32 v1, v4, v3, v5
	global_store_dwordx2 v[38:39], v[0:1], off offset:1536
	s_cbranch_scc0 .LBB0_977

; __device__ __forceinline__ u32x4 pack8(const f32x4 v0, const f32x4 v1) { u32x4 w; w.x = cvt_pk_bf16(v0[0], v0[1]); w.y = cvt_pk_bf16(v0[2], v0[3]); w.z = cvt_pk_bf16(v1[0], v1[1]); w.w = cvt_pk_bf16(v1[2], v1[3]); return w; }
; __device__ __forceinline__ void unpack8(const u32x4 w, f32x4& v0, f32x4& v1) { v0 = (f32x4){bf_lo(w.x), bf_hi(w.x), bf_lo(w.y), bf_hi(w.y)}; v1 = (f32x4){bf_lo(w.z), bf_hi(w.z), bf_lo(w.w), bf_hi(w.w)}; }
;     __device__ __forceinline__ void operator()(const f32x4 (&acc)[2][2][4][2], const Unit& u, int wr, int wc, int fr, int fq) const {
;         const int row0 = u.pm * BM + wr * 64 + fr, col0 = u.pn * BM + wc * 32 + 8 * fq;
; #pragma unroll
;         for (int ai = 0; ai < 2; ++ai)
; #pragma unroll
;             for (int m = 0; m < 4; ++m) { const int row = row0 + ai * HALF + m * 16;
;                 const size_t bo = base_grp_rows ? (size_t)(row / base_grp_rows) * base_grp_stride + (size_t)(row % base_grp_rows) * ldc : (size_t)row * ldc;
;                 const size_t oo = out_grp_rows ? (size_t)(row / out_grp_rows) * out_grp_stride + (size_t)(row % out_grp_rows) * ldc : (size_t)row * ldc;
; #pragma unroll
;                 for (int bj = 0; bj < 2; ++bj) { const int col = col0 + bj * HALF;
;                     f32x4 b0, b1;
;                     if constexpr (BASE_BF) unpack8(*(const u32x4*)((const bf16_t*)base + bo + col), b0, b1);
;                     else { b0 = *(const f32x4*)((const float*)base + bo + col); b1 = *(const f32x4*)((const float*)base + bo + col + 4); }
;                     *(u32x4*)(out + oo + col) = pack8(b0 + acc[ai][bj][m][0] * scale, b1 + acc[ai][bj][m][1] * scale); } }
.LBB0_1151:
	v_lshl_add_u32 v154, s49, 8, v161
	v_ashrrev_i32_e32 v155, 31, v154
	v_lshrrev_b32_e32 v156, 19, v155
	v_add_u32_e32 v153, v154, v156
	v_ashrrev_i32_e32 v158, 13, v153
	v_mul_i32_i24_e32 v153, 0x2000, v158
	v_sub_u32_e32 v168, v154, v153
	v_ashrrev_i32_e32 v169, 31, v168
	v_lshl_or_b32 v152, s50, 8, v163
	v_ashrrev_i32_e32 v159, 31, v158
	v_lshlrev_b64 v[168:169], 13, v[168:169]
	v_lshl_add_u64 v[168:169], s[44:45], 0, v[168:169]
	v_lshlrev_b64 v[158:159], 27, v[158:159]
	v_ashrrev_i32_e32 v153, 31, v152
	v_lshl_add_u64 v[158:159], v[168:169], 0, v[158:159]
	v_lshlrev_b64 v[152:153], 1, v[152:153]
	v_lshl_add_u64 v[158:159], v[158:159], 0, v[152:153]
	global_load_dwordx4 v[168:171], v[158:159], off nt
	s_mov_b64 s[18:19], -1
	s_and_b64 vcc, exec, s[38:39]
	s_waitcnt vmcnt(0)
	v_lshlrev_b32_e32 v172, 16, v168
	v_and_b32_e32 v173, 0xffff0000, v168
	v_lshlrev_b32_e32 v168, 16, v169
	v_and_b32_e32 v169, 0xffff0000, v169
	v_lshlrev_b32_e32 v174, 16, v170
	v_and_b32_e32 v175, 0xffff0000, v170
	v_lshlrev_b32_e32 v170, 16, v171
	v_and_b32_e32 v171, 0xffff0000, v171
	v_pk_add_f32 v[124:125], v[124:125], v[172:173]
	v_pk_add_f32 v[126:127], v[126:127], v[168:169]
	v_pk_add_f32 v[168:169], v[122:123], v[170:171]
	v_pk_add_f32 v[122:123], v[120:121], v[174:175]
	v_cvt_pk_bf16_f32 v120, v124, v125
	v_lshlrev_b64 v[124:125], 13, v[154:155]
	v_lshl_add_u64 v[124:125], s[10:11], 0, v[124:125]
	v_lshl_add_u64 v[124:125], v[124:125], 0, v[152:153]
	v_cvt_pk_bf16_f32 v121, v126, v127
	v_cvt_pk_bf16_f32 v122, v122, v123
	v_cvt_pk_bf16_f32 v123, v168, v169
	global_store_dwordx4 v[124:125], v[120:123], off
	global_load_dwordx4 v[120:123], v[158:159], off offset:256 nt
	s_waitcnt vmcnt(0)
	v_lshlrev_b32_e32 v126, 16, v120
	v_and_b32_e32 v127, 0xffff0000, v120
	v_lshlrev_b32_e32 v120, 16, v121
	v_and_b32_e32 v121, 0xffff0000, v121
	v_lshlrev_b32_e32 v158, 16, v122
	v_and_b32_e32 v159, 0xffff0000, v122
	v_lshlrev_b32_e32 v122, 16, v123
	v_and_b32_e32 v123, 0xffff0000, v123
	v_pk_add_f32 v[116:117], v[116:117], v[126:127]
	v_pk_add_f32 v[118:119], v[118:119], v[120:121]
	v_pk_add_f32 v[120:121], v[114:115], v[122:123]
	v_pk_add_f32 v[114:115], v[112:113], v[158:159]
	v_cvt_pk_bf16_f32 v112, v116, v117
	v_or_b32_e32 v116, 16, v154
	v_cvt_pk_bf16_f32 v113, v118, v119
	v_cvt_pk_bf16_f32 v114, v114, v115
	v_cvt_pk_bf16_f32 v115, v120, v121
	global_store_dwordx4 v[124:125], v[112:115], off offset:256
	v_ashrrev_i32_e32 v117, 31, v116
	s_nop 0
	v_add_u32_e32 v112, v116, v156
	v_ashrrev_i32_e32 v112, 13, v112
	v_mul_i32_i24_e32 v114, 0x2000, v112
	v_sub_u32_e32 v114, v116, v114
	v_ashrrev_i32_e32 v115, 31, v114
	v_ashrrev_i32_e32 v113, 31, v112
	v_lshlrev_b64 v[114:115], 13, v[114:115]
	v_lshl_add_u64 v[114:115], s[44:45], 0, v[114:115]
	v_lshlrev_b64 v[112:113], 27, v[112:113]
	v_lshl_add_u64 v[112:113], v[114:115], 0, v[112:113]
	v_lshl_add_u64 v[118:119], v[112:113], 0, v[152:153]
	global_load_dwordx4 v[112:115], v[118:119], off nt
	s_waitcnt vmcnt(0)
	v_lshlrev_b32_e32 v120, 16, v112
	v_and_b32_e32 v121, 0xffff0000, v112
	v_lshlrev_b32_e32 v112, 16, v113
	v_and_b32_e32 v113, 0xffff0000, v113
	v_lshlrev_b32_e32 v122, 16, v114
	v_and_b32_e32 v123, 0xffff0000, v114
	v_lshlrev_b32_e32 v114, 16, v115
	v_and_b32_e32 v115, 0xffff0000, v115
	v_pk_add_f32 v[108:109], v[108:109], v[120:121]
	v_pk_add_f32 v[110:111], v[110:111], v[112:113]
	v_pk_add_f32 v[112:113], v[106:107], v[114:115]
	v_pk_add_f32 v[106:107], v[104:105], v[122:123]
	v_cvt_pk_bf16_f32 v104, v108, v109
	v_lshlrev_b64 v[108:109], 13, v[116:117]
	v_lshl_add_u64 v[108:109], s[10:11], 0, v[108:109]
	v_lshl_add_u64 v[108:109], v[108:109], 0, v[152:153]
	v_cvt_pk_bf16_f32 v105, v110, v111
	v_cvt_pk_bf16_f32 v106, v106, v107
	v_cvt_pk_bf16_f32 v107, v112, v113
	global_store_dwordx4 v[108:109], v[104:107], off
	global_load_dwordx4 v[104:107], v[118:119], off offset:256 nt
	s_waitcnt vmcnt(0)
	v_lshlrev_b32_e32 v110, 16, v104
	v_and_b32_e32 v111, 0xffff0000, v104
	v_lshlrev_b32_e32 v104, 16, v105
	v_and_b32_e32 v105, 0xffff0000, v105
	v_lshlrev_b32_e32 v112, 16, v106
	v_and_b32_e32 v113, 0xffff0000, v106
	v_lshlrev_b32_e32 v106, 16, v107
	v_and_b32_e32 v107, 0xffff0000, v107
	v_pk_add_f32 v[100:101], v[100:101], v[110:111]
	v_pk_add_f32 v[102:103], v[102:103], v[104:105]
	v_pk_add_f32 v[104:105], v[98:99], v[106:107]
	v_pk_add_f32 v[98:99], v[96:97], v[112:113]
	v_cvt_pk_bf16_f32 v96, v100, v101
	v_or_b32_e32 v100, 32, v154
	v_cvt_pk_bf16_f32 v97, v102, v103
	v_cvt_pk_bf16_f32 v98, v98, v99
	v_cvt_pk_bf16_f32 v99, v104, v105
	global_store_dwordx4 v[108:109], v[96:99], off offset:256
	v_ashrrev_i32_e32 v101, 31, v100
	s_nop 0
	v_add_u32_e32 v96, v100, v156
	v_ashrrev_i32_e32 v96, 13, v96
	v_mul_i32_i24_e32 v98, 0x2000, v96
	v_sub_u32_e32 v98, v100, v98
	v_ashrrev_i32_e32 v99, 31, v98
	v_ashrrev_i32_e32 v97, 31, v96
	v_lshlrev_b64 v[98:99], 13, v[98:99]
	v_lshl_add_u64 v[98:99], s[44:45], 0, v[98:99]
	v_lshlrev_b64 v[96:97], 27, v[96:97]
	v_lshl_add_u64 v[96:97], v[98:99], 0, v[96:97]
	v_lshl_add_u64 v[102:103], v[96:97], 0, v[152:153]
	global_load_dwordx4 v[96:99], v[102:103], off nt
	s_waitcnt vmcnt(0)
	v_lshlrev_b32_e32 v104, 16, v96
	v_and_b32_e32 v105, 0xffff0000, v96
	v_lshlrev_b32_e32 v96, 16, v97
	v_and_b32_e32 v97, 0xffff0000, v97
	v_lshlrev_b32_e32 v106, 16, v98
	v_and_b32_e32 v107, 0xffff0000, v98
	v_lshlrev_b32_e32 v98, 16, v99
	v_and_b32_e32 v99, 0xffff0000, v99
	v_pk_add_f32 v[92:93], v[92:93], v[104:105]
	v_pk_add_f32 v[94:95], v[94:95], v[96:97]
	v_pk_add_f32 v[96:97], v[90:91], v[98:99]
	v_pk_add_f32 v[90:91], v[88:89], v[106:107]
	v_cvt_pk_bf16_f32 v88, v92, v93
	v_lshlrev_b64 v[92:93], 13, v[100:101]
	v_lshl_add_u64 v[92:93], s[10:11], 0, v[92:93]
	v_lshl_add_u64 v[92:93], v[92:93], 0, v[152:153]
	v_cvt_pk_bf16_f32 v89, v94, v95
	v_cvt_pk_bf16_f32 v90, v90, v91
	v_cvt_pk_bf16_f32 v91, v96, v97
	global_store_dwordx4 v[92:93], v[88:91], off
	global_load_dwordx4 v[88:91], v[102:103], off offset:256 nt
	s_waitcnt vmcnt(0)
; __device__ __forceinline__ u32x4 pack8(const f32x4 v0, const f32x4 v1) { u32x4 w; w.x = cvt_pk_bf16(v0[0], v0[1]); w.y = cvt_pk_bf16(v0[2], v0[3]); w.z = cvt_pk_bf16(v1[0], v1[1]); w.w = cvt_pk_bf16(v1[2], v1[3]); return w; }
; __device__ __forceinline__ void unpack8(const u32x4 w, f32x4& v0, f32x4& v1) { v0 = (f32x4){bf_lo(w.x), bf_hi(w.x), bf_lo(w.y), bf_hi(w.y)}; v1 = (f32x4){bf_lo(w.z), bf_hi(w.z), bf_lo(w.w), bf_hi(w.w)}; }
;     __device__ __forceinline__ void operator()(const f32x4 (&acc)[2][2][4][2], const Unit& u, int wr, int wc, int fr, int fq) const {
;     ...
;             for (int m = 0; m < 4; ++m) { const int row = row0 + ai * HALF + m * 16;
;                 const size_t bo = base_grp_rows ? (size_t)(row / base_grp_rows) * base_grp_stride + (size_t)(row % base_grp_rows) * ldc : (size_t)row * ldc;
;                 const size_t oo = out_grp_rows ? (size_t)(row / out_grp_rows) * out_grp_stride + (size_t)(row % out_grp_rows) * ldc : (size_t)row * ldc;
; #pragma unroll
;                 for (int bj = 0; bj < 2; ++bj) { const int col = col0 + bj * HALF;
;                     f32x4 b0, b1;
;                     if constexpr (BASE_BF) unpack8(*(const u32x4*)((const bf16_t*)base + bo + col), b0, b1);
;                     else { b0 = *(const f32x4*)((const float*)base + bo + col); b1 = *(const f32x4*)((const float*)base + bo + col + 4); }
;                     *(u32x4*)(out + oo + col) = pack8(b0 + acc[ai][bj][m][0] * scale, b1 + acc[ai][bj][m][1] * scale); } }
	v_lshlrev_b32_e32 v94, 16, v88
	v_and_b32_e32 v95, 0xffff0000, v88
	v_lshlrev_b32_e32 v88, 16, v89
	v_and_b32_e32 v89, 0xffff0000, v89
	v_lshlrev_b32_e32 v96, 16, v90
	v_and_b32_e32 v97, 0xffff0000, v90
	v_lshlrev_b32_e32 v90, 16, v91
	v_and_b32_e32 v91, 0xffff0000, v91
	v_pk_add_f32 v[84:85], v[84:85], v[94:95]
	v_pk_add_f32 v[86:87], v[86:87], v[88:89]
	v_pk_add_f32 v[88:89], v[82:83], v[90:91]
	v_pk_add_f32 v[82:83], v[80:81], v[96:97]
	v_cvt_pk_bf16_f32 v80, v84, v85
	v_or_b32_e32 v84, 48, v154
	v_cvt_pk_bf16_f32 v81, v86, v87
	v_cvt_pk_bf16_f32 v82, v82, v83
	v_cvt_pk_bf16_f32 v83, v88, v89
	global_store_dwordx4 v[92:93], v[80:83], off offset:256
	v_ashrrev_i32_e32 v85, 31, v84
	s_nop 0
	v_add_u32_e32 v80, v84, v156
	v_ashrrev_i32_e32 v80, 13, v80
	v_mul_i32_i24_e32 v82, 0x2000, v80
	v_sub_u32_e32 v82, v84, v82
	v_ashrrev_i32_e32 v83, 31, v82
	v_ashrrev_i32_e32 v81, 31, v80
	v_lshlrev_b64 v[82:83], 13, v[82:83]
	v_lshl_add_u64 v[82:83], s[44:45], 0, v[82:83]
	v_lshlrev_b64 v[80:81], 27, v[80:81]
	v_lshl_add_u64 v[80:81], v[82:83], 0, v[80:81]
	v_lshl_add_u64 v[86:87], v[80:81], 0, v[152:153]
	global_load_dwordx4 v[80:83], v[86:87], off nt
	s_waitcnt vmcnt(0)
	v_lshlrev_b32_e32 v88, 16, v80
	v_and_b32_e32 v89, 0xffff0000, v80
	v_lshlrev_b32_e32 v80, 16, v81
	v_and_b32_e32 v81, 0xffff0000, v81
	v_lshlrev_b32_e32 v90, 16, v82
	v_and_b32_e32 v91, 0xffff0000, v82
	v_lshlrev_b32_e32 v82, 16, v83
	v_and_b32_e32 v83, 0xffff0000, v83
	v_pk_add_f32 v[76:77], v[76:77], v[88:89]
	v_pk_add_f32 v[78:79], v[78:79], v[80:81]
	v_pk_add_f32 v[80:81], v[74:75], v[82:83]
	v_pk_add_f32 v[74:75], v[72:73], v[90:91]
	v_cvt_pk_bf16_f32 v72, v76, v77
	v_lshlrev_b64 v[76:77], 13, v[84:85]
	v_lshl_add_u64 v[76:77], s[10:11], 0, v[76:77]
	v_lshl_add_u64 v[76:77], v[76:77], 0, v[152:153]
	v_cvt_pk_bf16_f32 v73, v78, v79
	v_cvt_pk_bf16_f32 v74, v74, v75
	v_cvt_pk_bf16_f32 v75, v80, v81
	global_store_dwordx4 v[76:77], v[72:75], off
	global_load_dwordx4 v[72:75], v[86:87], off offset:256 nt
	s_waitcnt vmcnt(0)
	v_lshlrev_b32_e32 v78, 16, v72
	v_and_b32_e32 v79, 0xffff0000, v72
	v_lshlrev_b32_e32 v72, 16, v73
	v_and_b32_e32 v73, 0xffff0000, v73
	v_lshlrev_b32_e32 v80, 16, v74
	v_and_b32_e32 v81, 0xffff0000, v74
	v_lshlrev_b32_e32 v74, 16, v75
	v_and_b32_e32 v75, 0xffff0000, v75
	v_pk_add_f32 v[68:69], v[68:69], v[78:79]
	v_pk_add_f32 v[70:71], v[70:71], v[72:73]
	v_pk_add_f32 v[72:73], v[66:67], v[74:75]
	v_pk_add_f32 v[66:67], v[64:65], v[80:81]
	v_cvt_pk_bf16_f32 v64, v68, v69
	v_add_u32_e32 v68, 0x80, v154
	v_ashrrev_i32_e32 v69, 31, v68
	v_cvt_pk_bf16_f32 v65, v70, v71
	v_cvt_pk_bf16_f32 v66, v66, v67
	v_cvt_pk_bf16_f32 v67, v72, v73
	global_store_dwordx4 v[76:77], v[64:67], off offset:256
	s_nop 1
	v_lshrrev_b32_e32 v64, 19, v69
	v_add_u32_e32 v64, v68, v64
	v_ashrrev_i32_e32 v64, 13, v64
	v_mul_i32_i24_e32 v66, 0x2000, v64
	v_sub_u32_e32 v66, v68, v66
	v_ashrrev_i32_e32 v67, 31, v66
	v_ashrrev_i32_e32 v65, 31, v64
	v_lshlrev_b64 v[66:67], 13, v[66:67]
	v_lshl_add_u64 v[66:67], s[44:45], 0, v[66:67]
	v_lshlrev_b64 v[64:65], 27, v[64:65]
	v_lshl_add_u64 v[64:65], v[66:67], 0, v[64:65]
	v_lshl_add_u64 v[70:71], v[64:65], 0, v[152:153]
	global_load_dwordx4 v[64:67], v[70:71], off nt
	s_waitcnt vmcnt(0)
	v_lshlrev_b32_e32 v72, 16, v64
	v_and_b32_e32 v73, 0xffff0000, v64
	v_lshlrev_b32_e32 v64, 16, v65
	v_and_b32_e32 v65, 0xffff0000, v65
	v_lshlrev_b32_e32 v74, 16, v66
	v_and_b32_e32 v75, 0xffff0000, v66
	v_lshlrev_b32_e32 v66, 16, v67
	v_and_b32_e32 v67, 0xffff0000, v67
	v_pk_add_f32 v[60:61], v[60:61], v[72:73]
	v_pk_add_f32 v[62:63], v[62:63], v[64:65]
	v_pk_add_f32 v[64:65], v[58:59], v[66:67]
	v_pk_add_f32 v[58:59], v[56:57], v[74:75]
	v_cvt_pk_bf16_f32 v56, v60, v61
	v_lshlrev_b64 v[60:61], 13, v[68:69]
	v_lshl_add_u64 v[60:61], s[10:11], 0, v[60:61]
	v_lshl_add_u64 v[60:61], v[60:61], 0, v[152:153]
	v_cvt_pk_bf16_f32 v57, v62, v63
	v_cvt_pk_bf16_f32 v58, v58, v59
	v_cvt_pk_bf16_f32 v59, v64, v65
	global_store_dwordx4 v[60:61], v[56:59], off
	global_load_dwordx4 v[56:59], v[70:71], off offset:256 nt
	s_waitcnt vmcnt(0)
	v_lshlrev_b32_e32 v62, 16, v56
	v_and_b32_e32 v63, 0xffff0000, v56
	v_lshlrev_b32_e32 v56, 16, v57
	v_and_b32_e32 v57, 0xffff0000, v57
	v_lshlrev_b32_e32 v64, 16, v58
	v_and_b32_e32 v65, 0xffff0000, v58
	v_lshlrev_b32_e32 v58, 16, v59
	v_and_b32_e32 v59, 0xffff0000, v59
	v_pk_add_f32 v[52:53], v[52:53], v[62:63]
	v_pk_add_f32 v[54:55], v[54:55], v[56:57]
	v_pk_add_f32 v[56:57], v[50:51], v[58:59]
	v_pk_add_f32 v[50:51], v[48:49], v[64:65]
	v_cvt_pk_bf16_f32 v48, v52, v53
	v_add_u32_e32 v52, 0x90, v154
	v_ashrrev_i32_e32 v53, 31, v52
	v_cvt_pk_bf16_f32 v49, v54, v55
	v_cvt_pk_bf16_f32 v50, v50, v51
	v_cvt_pk_bf16_f32 v51, v56, v57
	global_store_dwordx4 v[60:61], v[48:51], off offset:256
	s_nop 1
	v_lshrrev_b32_e32 v48, 19, v53
	v_add_u32_e32 v48, v52, v48
	v_ashrrev_i32_e32 v48, 13, v48
	v_mul_i32_i24_e32 v50, 0x2000, v48
	v_sub_u32_e32 v50, v52, v50
	v_ashrrev_i32_e32 v51, 31, v50
	v_ashrrev_i32_e32 v49, 31, v48
	v_lshlrev_b64 v[50:51], 13, v[50:51]
	v_lshl_add_u64 v[50:51], s[44:45], 0, v[50:51]
	v_lshlrev_b64 v[48:49], 27, v[48:49]
	v_lshl_add_u64 v[48:49], v[50:51], 0, v[48:49]
	v_lshl_add_u64 v[54:55], v[48:49], 0, v[152:153]
	global_load_dwordx4 v[48:51], v[54:55], off nt
	s_waitcnt vmcnt(0)
; __device__ __forceinline__ u32x4 pack8(const f32x4 v0, const f32x4 v1) { u32x4 w; w.x = cvt_pk_bf16(v0[0], v0[1]); w.y = cvt_pk_bf16(v0[2], v0[3]); w.z = cvt_pk_bf16(v1[0], v1[1]); w.w = cvt_pk_bf16(v1[2], v1[3]); return w; }
; __device__ __forceinline__ void unpack8(const u32x4 w, f32x4& v0, f32x4& v1) { v0 = (f32x4){bf_lo(w.x), bf_hi(w.x), bf_lo(w.y), bf_hi(w.y)}; v1 = (f32x4){bf_lo(w.z), bf_hi(w.z), bf_lo(w.w), bf_hi(w.w)}; }
;     __device__ __forceinline__ void operator()(const f32x4 (&acc)[2][2][4][2], const Unit& u, int wr, int wc, int fr, int fq) const {
;     ...
;             for (int m = 0; m < 4; ++m) { const int row = row0 + ai * HALF + m * 16;
;                 const size_t bo = base_grp_rows ? (size_t)(row / base_grp_rows) * base_grp_stride + (size_t)(row % base_grp_rows) * ldc : (size_t)row * ldc;
;                 const size_t oo = out_grp_rows ? (size_t)(row / out_grp_rows) * out_grp_stride + (size_t)(row % out_grp_rows) * ldc : (size_t)row * ldc;
; #pragma unroll
;                 for (int bj = 0; bj < 2; ++bj) { const int col = col0 + bj * HALF;
;                     f32x4 b0, b1;
;                     if constexpr (BASE_BF) unpack8(*(const u32x4*)((const bf16_t*)base + bo + col), b0, b1);
;                     else { b0 = *(const f32x4*)((const float*)base + bo + col); b1 = *(const f32x4*)((const float*)base + bo + col + 4); }
;                     *(u32x4*)(out + oo + col) = pack8(b0 + acc[ai][bj][m][0] * scale, b1 + acc[ai][bj][m][1] * scale); } }
	v_lshlrev_b32_e32 v56, 16, v48
	v_and_b32_e32 v57, 0xffff0000, v48
	v_lshlrev_b32_e32 v48, 16, v49
	v_and_b32_e32 v49, 0xffff0000, v49
	v_lshlrev_b32_e32 v58, 16, v50
	v_and_b32_e32 v59, 0xffff0000, v50
	v_lshlrev_b32_e32 v50, 16, v51
	v_and_b32_e32 v51, 0xffff0000, v51
	v_pk_add_f32 v[44:45], v[44:45], v[56:57]
	v_pk_add_f32 v[46:47], v[46:47], v[48:49]
	v_pk_add_f32 v[48:49], v[42:43], v[50:51]
	v_pk_add_f32 v[42:43], v[40:41], v[58:59]
	v_cvt_pk_bf16_f32 v40, v44, v45
	v_lshlrev_b64 v[44:45], 13, v[52:53]
	v_lshl_add_u64 v[44:45], s[10:11], 0, v[44:45]
	v_lshl_add_u64 v[44:45], v[44:45], 0, v[152:153]
	v_cvt_pk_bf16_f32 v41, v46, v47
	v_cvt_pk_bf16_f32 v42, v42, v43
	v_cvt_pk_bf16_f32 v43, v48, v49
	global_store_dwordx4 v[44:45], v[40:43], off
	global_load_dwordx4 v[40:43], v[54:55], off offset:256 nt
	s_waitcnt vmcnt(0)
	v_lshlrev_b32_e32 v46, 16, v40
	v_and_b32_e32 v47, 0xffff0000, v40
	v_lshlrev_b32_e32 v40, 16, v41
	v_and_b32_e32 v41, 0xffff0000, v41
	v_lshlrev_b32_e32 v48, 16, v42
	v_and_b32_e32 v49, 0xffff0000, v42
	v_lshlrev_b32_e32 v42, 16, v43
	v_and_b32_e32 v43, 0xffff0000, v43
	v_pk_add_f32 v[36:37], v[36:37], v[46:47]
	v_pk_add_f32 v[38:39], v[38:39], v[40:41]
	v_pk_add_f32 v[40:41], v[34:35], v[42:43]
	v_pk_add_f32 v[34:35], v[32:33], v[48:49]
	v_cvt_pk_bf16_f32 v32, v36, v37
	v_add_u32_e32 v36, 0xa0, v154
	v_ashrrev_i32_e32 v37, 31, v36
	v_cvt_pk_bf16_f32 v33, v38, v39
	v_cvt_pk_bf16_f32 v34, v34, v35
	v_cvt_pk_bf16_f32 v35, v40, v41
	global_store_dwordx4 v[44:45], v[32:35], off offset:256
	s_nop 1
	v_lshrrev_b32_e32 v32, 19, v37
	v_add_u32_e32 v32, v36, v32
	v_ashrrev_i32_e32 v32, 13, v32
	v_mul_i32_i24_e32 v34, 0x2000, v32
	v_sub_u32_e32 v34, v36, v34
	v_ashrrev_i32_e32 v35, 31, v34
	v_ashrrev_i32_e32 v33, 31, v32
	v_lshlrev_b64 v[34:35], 13, v[34:35]
	v_lshl_add_u64 v[34:35], s[44:45], 0, v[34:35]
	v_lshlrev_b64 v[32:33], 27, v[32:33]
	v_lshl_add_u64 v[32:33], v[34:35], 0, v[32:33]
	v_lshl_add_u64 v[38:39], v[32:33], 0, v[152:153]
	global_load_dwordx4 v[32:35], v[38:39], off nt
	s_waitcnt vmcnt(0)
	v_lshlrev_b32_e32 v40, 16, v32
	v_and_b32_e32 v41, 0xffff0000, v32
	v_lshlrev_b32_e32 v32, 16, v33
	v_and_b32_e32 v33, 0xffff0000, v33
	v_lshlrev_b32_e32 v42, 16, v34
	v_and_b32_e32 v43, 0xffff0000, v34
	v_lshlrev_b32_e32 v34, 16, v35
	v_and_b32_e32 v35, 0xffff0000, v35
	v_pk_add_f32 v[28:29], v[28:29], v[40:41]
	v_pk_add_f32 v[30:31], v[30:31], v[32:33]
	v_pk_add_f32 v[32:33], v[26:27], v[34:35]
	v_pk_add_f32 v[26:27], v[24:25], v[42:43]
	v_cvt_pk_bf16_f32 v24, v28, v29
	v_lshlrev_b64 v[28:29], 13, v[36:37]
	v_lshl_add_u64 v[28:29], s[10:11], 0, v[28:29]
	v_lshl_add_u64 v[28:29], v[28:29], 0, v[152:153]
	v_cvt_pk_bf16_f32 v25, v30, v31
	v_cvt_pk_bf16_f32 v26, v26, v27
	v_cvt_pk_bf16_f32 v27, v32, v33
	global_store_dwordx4 v[28:29], v[24:27], off
	global_load_dwordx4 v[24:27], v[38:39], off offset:256 nt
	s_waitcnt vmcnt(0)
	v_lshlrev_b32_e32 v30, 16, v24
	v_and_b32_e32 v31, 0xffff0000, v24
	v_lshlrev_b32_e32 v24, 16, v25
	v_and_b32_e32 v25, 0xffff0000, v25
	v_lshlrev_b32_e32 v32, 16, v26
	v_and_b32_e32 v33, 0xffff0000, v26
	v_lshlrev_b32_e32 v26, 16, v27
	v_and_b32_e32 v27, 0xffff0000, v27
	v_pk_add_f32 v[20:21], v[20:21], v[30:31]
	v_pk_add_f32 v[22:23], v[22:23], v[24:25]
	v_pk_add_f32 v[24:25], v[18:19], v[26:27]
	v_pk_add_f32 v[18:19], v[16:17], v[32:33]
	v_cvt_pk_bf16_f32 v16, v20, v21
	v_add_u32_e32 v20, 0xb0, v154
	v_ashrrev_i32_e32 v21, 31, v20
	v_cvt_pk_bf16_f32 v17, v22, v23
	v_cvt_pk_bf16_f32 v18, v18, v19
	v_cvt_pk_bf16_f32 v19, v24, v25
	global_store_dwordx4 v[28:29], v[16:19], off offset:256
	s_nop 1
	v_lshrrev_b32_e32 v16, 19, v21
	v_add_u32_e32 v16, v20, v16
	v_ashrrev_i32_e32 v16, 13, v16
	v_mul_i32_i24_e32 v18, 0x2000, v16
	v_sub_u32_e32 v18, v20, v18
	v_ashrrev_i32_e32 v19, 31, v18
	v_ashrrev_i32_e32 v17, 31, v16
	v_lshlrev_b64 v[18:19], 13, v[18:19]
	v_lshl_add_u64 v[18:19], s[44:45], 0, v[18:19]
	v_lshlrev_b64 v[16:17], 27, v[16:17]
	v_lshl_add_u64 v[16:17], v[18:19], 0, v[16:17]
	v_lshl_add_u64 v[22:23], v[16:17], 0, v[152:153]
	global_load_dwordx4 v[16:19], v[22:23], off nt
	s_waitcnt vmcnt(0)
	v_lshlrev_b32_e32 v24, 16, v16
	v_and_b32_e32 v25, 0xffff0000, v16
	v_lshlrev_b32_e32 v16, 16, v17
	v_and_b32_e32 v17, 0xffff0000, v17
	v_lshlrev_b32_e32 v26, 16, v18
	v_and_b32_e32 v27, 0xffff0000, v18
	v_lshlrev_b32_e32 v18, 16, v19
	v_and_b32_e32 v19, 0xffff0000, v19
	v_pk_add_f32 v[12:13], v[12:13], v[24:25]
	v_pk_add_f32 v[14:15], v[14:15], v[16:17]
	v_pk_add_f32 v[16:17], v[10:11], v[18:19]
	v_pk_add_f32 v[10:11], v[8:9], v[26:27]
	v_cvt_pk_bf16_f32 v8, v12, v13
	v_lshlrev_b64 v[12:13], 13, v[20:21]
	v_lshl_add_u64 v[12:13], s[10:11], 0, v[12:13]
	v_lshl_add_u64 v[12:13], v[12:13], 0, v[152:153]
	v_cvt_pk_bf16_f32 v9, v14, v15
	v_cvt_pk_bf16_f32 v10, v10, v11
	v_cvt_pk_bf16_f32 v11, v16, v17
	global_store_dwordx4 v[12:13], v[8:11], off
	global_load_dwordx4 v[8:11], v[22:23], off offset:256 nt
	s_waitcnt vmcnt(0)
	v_lshlrev_b32_e32 v14, 16, v8
	v_and_b32_e32 v15, 0xffff0000, v8
	v_lshlrev_b32_e32 v8, 16, v9
	v_and_b32_e32 v9, 0xffff0000, v9
	v_lshlrev_b32_e32 v16, 16, v10
	v_and_b32_e32 v17, 0xffff0000, v10
	v_lshlrev_b32_e32 v10, 16, v11
	v_and_b32_e32 v11, 0xffff0000, v11
	v_pk_add_f32 v[6:7], v[6:7], v[8:9]
	v_pk_add_f32 v[8:9], v[2:3], v[10:11]
	v_pk_add_f32 v[2:3], v[0:1], v[16:17]
	v_pk_add_f32 v[4:5], v[4:5], v[14:15]
	s_nop 0
	v_cvt_pk_bf16_f32 v0, v4, v5
	v_cvt_pk_bf16_f32 v1, v6, v7
	v_cvt_pk_bf16_f32 v2, v2, v3
	v_cvt_pk_bf16_f32 v3, v8, v9
	global_store_dwordx4 v[12:13], v[0:3], off offset:256
	s_cbranch_vccnz .LBB0_1137
	s_andn2_b64 vcc, exec, s[8:9]
	s_cbranch_vccnz .LBB0_1136
	s_barrier
	s_branch .LBB0_1136
